# cross-lane xor-16/xor-32 adds in EpiResid/swiglu/w_in/q epilogues use v_permlane16/32_swap instead of ds_bpermute round trips
# speedup vs baseline: 1.0087x; 1.0087x over previous
.LBB7_360:
	v_and_b32_e32 v131, 64, v163
	v_xor_b32_e32 v130, 16, v163
	v_add_u32_e32 v131, 64, v131
	v_cmp_lt_i32_e32 vcc, v130, v131
	v_lshl_add_u32 v132, s38, 8, v142
	v_ashrrev_i32_e32 v133, 31, v132
	v_cndmask_b32_e32 v130, v163, v130, vcc
	v_lshlrev_b32_e32 v183, 2, v130
	v_xor_b32_e32 v130, 32, v163
	v_cmp_lt_i32_e32 vcc, v130, v131
	v_or_b32_e32 v172, 16, v132
	v_ashrrev_i32_e32 v173, 31, v172
	v_cndmask_b32_e32 v130, v163, v130, vcc
	v_lshlrev_b32_e32 v181, 2, v130
	v_lshlrev_b64 v[130:131], 6, v[132:133]
	v_lshl_add_u64 v[130:131], v[144:145], 0, v[130:131]
	v_lshlrev_b64 v[172:173], 6, v[172:173]
	v_lshl_add_u64 v[172:173], v[144:145], 0, v[172:173]
	s_lshl_b32 s9, s10, 7
	s_mov_b32 s10, 0x358637bd
	v_mov_b64_e32 v[190:191], s[10:11]
	s_movk_i32 s10, 0x2000
	s_or_b32 s9, s9, s96
	s_ashr_i32 s16, s9, 6
	s_ashr_i32 s17, s16, 31
	s_mul_i32 s13, s38, 0x160000
	s_lshl_b64 s[16:17], s[16:17], 15
	s_add_u32 s9, s70, s13
	s_waitcnt vmcnt(0)
	v_mov_b64_e32 v[184:185], v[204:205]
	v_mov_b64_e32 v[186:187], v[206:207]
	v_mov_b32_e32 v170, v185
	v_mov_b32_e32 v171, v186
	v_mov_b32_e32 v185, v187
	v_pk_add_f32 v[170:171], v[170:171], v[184:185]
	v_mov_b64_e32 v[184:185], v[208:209]
	v_mov_b64_e32 v[186:187], v[210:211]
	v_mov_b32_e32 v172, v185
	v_mov_b32_e32 v173, v186
	v_mov_b32_e32 v185, v187
	v_pk_add_f32 v[172:173], v[172:173], v[184:185]
	v_mov_b32_e32 v185, v170
	v_mov_b32_e32 v184, v172
	v_mov_b32_e32 v170, v173
	v_pk_add_f32 v[170:171], v[184:185], v[170:171]
	v_mov_b32_e32 v173, v171
	s_nop 1
	v_permlane16_swap_b32_e32 v171, v173
	v_mov_b32_e32 v172, v170
	s_nop 1
	v_permlane16_swap_b32_e32 v170, v172
	s_waitcnt lgkmcnt(0)
	v_pk_add_f32 v[170:171], v[170:171], v[172:173]
	v_mov_b32_e32 v173, v171
	s_nop 1
	v_permlane32_swap_b32_e32 v171, v173
	v_mov_b32_e32 v172, v170
	s_nop 1
	v_permlane32_swap_b32_e32 v170, v172
	s_waitcnt lgkmcnt(0)
	v_pk_add_f32 v[170:171], v[170:171], v[172:173]
	s_nop 0
	v_pk_fma_f32 v[170:171], v[170:171], s[26:27], v[190:191] op_sel_hi:[1,0,0]
	s_nop 0
	v_mul_f32_e32 v133, 0x4b800000, v171
	v_cmp_gt_f32_e64 s[42:43], s11, v171
	v_cmp_gt_f32_e32 vcc, s11, v170
	s_nop 0
	v_cndmask_b32_e64 v133, v171, v133, s[42:43]
	v_rsq_f32_e32 v133, v133
	s_nop 0
	v_mul_f32_e32 v171, 0x45800000, v133
	v_cndmask_b32_e64 v188, v133, v171, s[42:43]
	v_mul_f32_e32 v133, 0x4b800000, v170
	v_cndmask_b32_e32 v133, v170, v133, vcc
	v_rsq_f32_e32 v133, v133
	v_pk_mul_f32 v[126:127], v[126:127], v[188:189] op_sel_hi:[1,0]
	v_pk_mul_f32 v[122:123], v[122:123], v[188:189] op_sel_hi:[1,0]
	v_pk_mul_f32 v[124:125], v[124:125], v[188:189] op_sel_hi:[1,0]
	v_mul_f32_e32 v170, 0x45800000, v133
	v_cndmask_b32_e32 v186, v133, v170, vcc
	v_or_b32_e32 v170, 32, v132
	v_ashrrev_i32_e32 v171, 31, v170
	v_lshlrev_b64 v[170:171], 6, v[170:171]
	v_lshl_add_u64 v[170:171], v[144:145], 0, v[170:171]
	v_or_b32_e32 v132, 48, v132
	v_ashrrev_i32_e32 v133, 31, v132
	v_lshlrev_b64 v[132:133], 6, v[132:133]
	v_lshl_add_u64 v[132:133], v[144:145], 0, v[132:133]
	v_pk_mul_f32 v[122:123], v[126:127], v[122:123]
	v_pk_mul_f32 v[118:119], v[118:119], v[188:189] op_sel_hi:[1,0]
	v_pk_mul_f32 v[114:115], v[114:115], v[188:189] op_sel_hi:[1,0]
	v_pk_mul_f32 v[116:117], v[116:117], v[188:189] op_sel_hi:[1,0]
	v_pk_mul_f32 v[114:115], v[118:119], v[114:115]
	v_pk_mul_f32 v[110:111], v[110:111], v[186:187] op_sel_hi:[1,0]
	v_pk_mul_f32 v[106:107], v[106:107], v[186:187] op_sel_hi:[1,0]
	v_pk_mul_f32 v[108:109], v[108:109], v[186:187] op_sel_hi:[1,0]
	v_pk_mul_f32 v[106:107], v[110:111], v[106:107]
	v_pk_mul_f32 v[102:103], v[102:103], v[186:187] op_sel_hi:[1,0]
	v_pk_mul_f32 v[98:99], v[98:99], v[186:187] op_sel_hi:[1,0]
	v_pk_mul_f32 v[100:101], v[100:101], v[186:187] op_sel_hi:[1,0]
	v_pk_mul_f32 v[98:99], v[102:103], v[98:99]
	v_mov_b64_e32 v[192:193], v[212:213]
	v_mov_b64_e32 v[194:195], v[214:215]
	v_mov_b32_e32 v170, v193
	v_mov_b32_e32 v171, v194
	v_mov_b32_e32 v193, v195
	v_pk_add_f32 v[170:171], v[170:171], v[192:193]
	v_mov_b64_e32 v[192:193], v[216:217]
	v_mov_b64_e32 v[194:195], v[218:219]
	v_mov_b32_e32 v173, v170
	v_mov_b32_e32 v132, v193
	v_mov_b32_e32 v133, v194
	v_mov_b32_e32 v193, v195
	v_pk_add_f32 v[132:133], v[132:133], v[192:193]
	s_nop 0
	v_mov_b32_e32 v172, v132
	v_mov_b32_e32 v170, v133
	v_pk_add_f32 v[132:133], v[172:173], v[170:171]
	v_mov_b32_e32 v171, v133
	s_nop 1
	v_permlane16_swap_b32_e32 v133, v171
	v_mov_b32_e32 v170, v132
	s_nop 1
	v_permlane16_swap_b32_e32 v132, v170
	s_waitcnt lgkmcnt(0)
	v_pk_add_f32 v[132:133], v[132:133], v[170:171]
	v_mov_b32_e32 v171, v133
	s_nop 1
	v_permlane32_swap_b32_e32 v133, v171
	v_mov_b32_e32 v170, v132
	s_nop 1
	v_permlane32_swap_b32_e32 v132, v170
	s_waitcnt lgkmcnt(0)
	v_pk_add_f32 v[132:133], v[132:133], v[170:171]
	s_nop 0
	v_pk_fma_f32 v[132:133], v[132:133], s[26:27], v[190:191] op_sel_hi:[1,0,0]
	s_nop 0
	v_mul_f32_e32 v170, 0x4b800000, v133
	v_cmp_gt_f32_e64 s[42:43], s11, v133
	v_cmp_gt_f32_e32 vcc, s11, v132
	s_nop 0
	v_cndmask_b32_e64 v133, v133, v170, s[42:43]
	v_rsq_f32_e32 v133, v133
	s_nop 0
	v_mul_f32_e32 v170, 0x45800000, v133
	v_cndmask_b32_e64 v184, v133, v170, s[42:43]
	v_mul_f32_e32 v133, 0x4b800000, v132
	v_cndmask_b32_e32 v132, v132, v133, vcc
	v_rsq_f32_e32 v132, v132
	v_pk_mul_f32 v[94:95], v[94:95], v[184:185] op_sel_hi:[1,0]
	v_pk_mul_f32 v[90:91], v[90:91], v[184:185] op_sel_hi:[1,0]
	v_pk_mul_f32 v[92:93], v[92:93], v[184:185] op_sel_hi:[1,0]
	v_mul_f32_e32 v133, 0x45800000, v132
	v_cndmask_b32_e32 v182, v132, v133, vcc
	v_add_co_u32_e32 v170, vcc, s10, v130
	s_mul_hi_i32 s10, s38, 0x160000
	s_nop 0
	v_addc_co_u32_e32 v171, vcc, 0, v131, vcc
	s_addc_u32 s10, s71, s10
	s_add_u32 s16, s9, s16
	s_addc_u32 s17, s10, s17
	v_pk_mul_f32 v[90:91], v[94:95], v[90:91]
	v_pk_mul_f32 v[86:87], v[86:87], v[184:185] op_sel_hi:[1,0]
	v_pk_mul_f32 v[82:83], v[82:83], v[184:185] op_sel_hi:[1,0]
	v_pk_mul_f32 v[84:85], v[84:85], v[184:185] op_sel_hi:[1,0]
	v_pk_mul_f32 v[82:83], v[86:87], v[82:83]
	v_pk_mul_f32 v[78:79], v[78:79], v[182:183] op_sel_hi:[1,0]
	v_pk_mul_f32 v[74:75], v[74:75], v[182:183] op_sel_hi:[1,0]
	v_pk_mul_f32 v[76:77], v[76:77], v[182:183] op_sel_hi:[1,0]
	v_pk_mul_f32 v[74:75], v[78:79], v[74:75]
	v_pk_mul_f32 v[70:71], v[70:71], v[182:183] op_sel_hi:[1,0]
	v_pk_mul_f32 v[66:67], v[66:67], v[182:183] op_sel_hi:[1,0]
	v_pk_mul_f32 v[68:69], v[68:69], v[182:183] op_sel_hi:[1,0]
	v_pk_mul_f32 v[66:67], v[70:71], v[66:67]
	v_mov_b64_e32 v[130:131], v[220:221]
	v_mov_b64_e32 v[132:133], v[222:223]
	v_mov_b32_e32 v172, v131
	v_mov_b32_e32 v173, v132
	v_mov_b32_e32 v131, v133
	v_pk_add_f32 v[172:173], v[172:173], v[130:131]
	v_mov_b64_e32 v[130:131], v[224:225]
	v_mov_b64_e32 v[132:133], v[226:227]
	v_mov_b32_e32 v192, v131
	v_mov_b32_e32 v193, v132
	v_mov_b32_e32 v131, v133
	v_pk_add_f32 v[130:131], v[192:193], v[130:131]
	v_mov_b32_e32 v133, v172
	v_mov_b32_e32 v132, v130
	v_mov_b32_e32 v172, v131
	v_pk_add_f32 v[130:131], v[132:133], v[172:173]
	v_mov_b32_e32 v133, v131
	s_nop 1
	v_permlane16_swap_b32_e32 v131, v133
	v_mov_b32_e32 v132, v130
	s_nop 1
	v_permlane16_swap_b32_e32 v130, v132
	s_waitcnt lgkmcnt(0)
	v_pk_add_f32 v[130:131], v[130:131], v[132:133]
	v_mov_b32_e32 v133, v131
	s_nop 1
	v_permlane32_swap_b32_e32 v131, v133
	v_mov_b32_e32 v132, v130
	s_nop 1
	v_permlane32_swap_b32_e32 v130, v132
	s_waitcnt lgkmcnt(0)
	v_pk_add_f32 v[130:131], v[130:131], v[132:133]
	s_nop 0
	v_pk_fma_f32 v[130:131], v[130:131], s[26:27], v[190:191] op_sel_hi:[1,0,0]
	s_nop 0
	v_mul_f32_e32 v132, 0x4b800000, v131
	v_cmp_gt_f32_e64 s[42:43], s11, v131
	v_cmp_gt_f32_e32 vcc, s11, v130
	s_nop 0
	v_cndmask_b32_e64 v131, v131, v132, s[42:43]
	v_rsq_f32_e32 v131, v131
	s_nop 0
	v_mul_f32_e32 v132, 0x45800000, v131
	v_cndmask_b32_e64 v180, v131, v132, s[42:43]
	v_mul_f32_e32 v131, 0x4b800000, v130
	v_cndmask_b32_e32 v130, v130, v131, vcc
	v_rsq_f32_e32 v130, v130
	v_pk_mul_f32 v[62:63], v[62:63], v[180:181] op_sel_hi:[1,0]
	v_pk_mul_f32 v[58:59], v[58:59], v[180:181] op_sel_hi:[1,0]
	v_pk_mul_f32 v[60:61], v[60:61], v[180:181] op_sel_hi:[1,0]
	v_mul_f32_e32 v131, 0x45800000, v130
	v_cndmask_b32_e32 v178, v130, v131, vcc
	v_pk_mul_f32 v[58:59], v[62:63], v[58:59]
	v_pk_mul_f32 v[54:55], v[54:55], v[180:181] op_sel_hi:[1,0]
	v_pk_mul_f32 v[50:51], v[50:51], v[180:181] op_sel_hi:[1,0]
	v_pk_mul_f32 v[52:53], v[52:53], v[180:181] op_sel_hi:[1,0]
	v_pk_mul_f32 v[50:51], v[54:55], v[50:51]
	v_pk_mul_f32 v[46:47], v[46:47], v[178:179] op_sel_hi:[1,0]
	v_pk_mul_f32 v[42:43], v[42:43], v[178:179] op_sel_hi:[1,0]
	v_pk_mul_f32 v[44:45], v[44:45], v[178:179] op_sel_hi:[1,0]
	v_pk_mul_f32 v[42:43], v[46:47], v[42:43]
	v_pk_mul_f32 v[38:39], v[38:39], v[178:179] op_sel_hi:[1,0]
	v_pk_mul_f32 v[34:35], v[34:35], v[178:179] op_sel_hi:[1,0]
	v_pk_mul_f32 v[36:37], v[36:37], v[178:179] op_sel_hi:[1,0]
	v_pk_mul_f32 v[34:35], v[38:39], v[34:35]
	v_mov_b64_e32 v[130:131], v[228:229]
	v_mov_b64_e32 v[132:133], v[230:231]
	v_mov_b32_e32 v172, v131
	v_mov_b32_e32 v173, v132
	v_mov_b32_e32 v131, v133
	v_pk_add_f32 v[192:193], v[172:173], v[130:131]
	v_mov_b64_e32 v[130:131], v[232:233]
	v_mov_b64_e32 v[132:133], v[234:235]
	v_mov_b32_e32 v170, v131
	v_mov_b32_e32 v171, v132
	v_mov_b32_e32 v131, v133
	v_pk_add_f32 v[130:131], v[170:171], v[130:131]
	v_pk_mul_f32 v[170:171], v[126:127], s[30:31] op_sel_hi:[1,0]
	v_pk_mul_f32 v[126:127], v[128:129], v[188:189] op_sel_hi:[1,0]
	v_exp_f32_e32 v170, v170
	v_pk_mul_f32 v[128:129], v[126:127], s[30:31] op_sel_hi:[1,0]
	v_exp_f32_e32 v171, v171
	v_exp_f32_e32 v128, v128
	v_exp_f32_e32 v129, v129
	v_pk_mul_f32 v[124:125], v[126:127], v[124:125]
	v_pk_add_f32 v[170:171], v[170:171], 1.0 op_sel_hi:[1,0]
	v_mov_b32_e32 v132, v130
	v_pk_add_f32 v[128:129], v[128:129], 1.0 op_sel_hi:[1,0]
	v_rcp_f32_e32 v170, v170
	v_rcp_f32_e32 v171, v171
	v_rcp_f32_e32 v128, v128
	v_rcp_f32_e32 v129, v129
	v_mov_b32_e32 v133, v192
	v_pk_mul_f32 v[122:123], v[122:123], v[170:171]
	v_mov_b32_e32 v192, v131
	v_pk_mul_f32 v[124:125], v[124:125], v[128:129]
	v_cvt_pk_bf16_f32 v122, v122, v123
	v_pk_add_f32 v[130:131], v[132:133], v[192:193]
	v_cvt_pk_bf16_f32 v123, v124, v125
	v_pk_mul_f32 v[124:125], v[118:119], s[30:31] op_sel_hi:[1,0]
	v_mov_b32_e32 v133, v131
	s_nop 1
	v_permlane16_swap_b32_e32 v131, v133
	v_exp_f32_e32 v124, v124
	v_exp_f32_e32 v125, v125
	v_mov_b32_e32 v132, v130
	s_nop 1
	v_permlane16_swap_b32_e32 v130, v132
	v_pk_add_f32 v[124:125], v[124:125], 1.0 op_sel_hi:[1,0]
	s_nop 0
	v_rcp_f32_e32 v124, v124
	v_rcp_f32_e32 v125, v125
	s_waitcnt lgkmcnt(0)
	v_pk_add_f32 v[130:131], v[130:131], v[132:133]
	v_mov_b32_e32 v133, v131
	s_nop 1
	v_permlane32_swap_b32_e32 v131, v133
	v_mov_b32_e32 v132, v130
	s_nop 1
	v_permlane32_swap_b32_e32 v130, v132
	v_pk_mul_f32 v[114:115], v[114:115], v[124:125]
	s_waitcnt lgkmcnt(0)
	v_pk_add_f32 v[130:131], v[130:131], v[132:133]
	v_cvt_pk_bf16_f32 v124, v114, v115
	v_pk_mul_f32 v[114:115], v[120:121], v[188:189] op_sel_hi:[1,0]
	v_pk_fma_f32 v[130:131], v[130:131], s[26:27], v[190:191] op_sel_hi:[1,0,0]
	v_pk_mul_f32 v[118:119], v[114:115], s[30:31] op_sel_hi:[1,0]
	v_pk_mul_f32 v[114:115], v[114:115], v[116:117]
	v_exp_f32_e32 v118, v118
	v_exp_f32_e32 v119, v119
	v_mul_f32_e32 v132, 0x4b800000, v131
	v_cmp_gt_f32_e64 s[42:43], s11, v131
	v_cmp_gt_f32_e32 vcc, s11, v130
	v_pk_add_f32 v[118:119], v[118:119], 1.0 op_sel_hi:[1,0]
	v_cndmask_b32_e64 v131, v131, v132, s[42:43]
	v_rcp_f32_e32 v118, v118
	v_rcp_f32_e32 v119, v119
	v_rsq_f32_e32 v131, v131
	v_pk_mul_f32 v[114:115], v[114:115], v[118:119]
	s_nop 0
	v_cvt_pk_bf16_f32 v125, v114, v115
	v_lshl_add_u64 v[114:115], s[16:17], 0, v[146:147]
	v_lshl_add_u64 v[114:115], v[114:115], 0, v[0:1]
	global_store_dwordx4 v[114:115], v[122:125], off nt
	v_pk_mul_f32 v[114:115], v[110:111], s[30:31] op_sel_hi:[1,0]
	v_pk_mul_f32 v[110:111], v[112:113], v[186:187] op_sel_hi:[1,0]
	v_exp_f32_e32 v114, v114
	v_pk_mul_f32 v[112:113], v[110:111], s[30:31] op_sel_hi:[1,0]
	v_exp_f32_e32 v115, v115
	v_exp_f32_e32 v112, v112
	v_exp_f32_e32 v113, v113
	v_pk_mul_f32 v[108:109], v[110:111], v[108:109]
	v_pk_add_f32 v[114:115], v[114:115], 1.0 op_sel_hi:[1,0]
	v_pk_add_f32 v[112:113], v[112:113], 1.0 op_sel_hi:[1,0]
	v_rcp_f32_e32 v114, v114
	v_rcp_f32_e32 v115, v115
	v_rcp_f32_e32 v112, v112
	v_rcp_f32_e32 v113, v113
	v_mul_f32_e32 v132, 0x45800000, v131
	v_pk_mul_f32 v[106:107], v[106:107], v[114:115]
	v_cndmask_b32_e64 v132, v131, v132, s[42:43]
	v_pk_mul_f32 v[108:109], v[108:109], v[112:113]
	v_cvt_pk_bf16_f32 v106, v106, v107
	v_pk_mul_f32 v[30:31], v[30:31], v[132:133] op_sel_hi:[1,0]
	v_cvt_pk_bf16_f32 v107, v108, v109
	v_pk_mul_f32 v[108:109], v[102:103], s[30:31] op_sel_hi:[1,0]
	v_pk_mul_f32 v[26:27], v[26:27], v[132:133] op_sel_hi:[1,0]
	v_exp_f32_e32 v108, v108
	v_exp_f32_e32 v109, v109
	v_pk_mul_f32 v[26:27], v[30:31], v[26:27]
	v_pk_mul_f32 v[28:29], v[28:29], v[132:133] op_sel_hi:[1,0]
	v_pk_mul_f32 v[22:23], v[22:23], v[132:133] op_sel_hi:[1,0]
	v_pk_add_f32 v[108:109], v[108:109], 1.0 op_sel_hi:[1,0]
	v_pk_mul_f32 v[18:19], v[18:19], v[132:133] op_sel_hi:[1,0]
	v_rcp_f32_e32 v108, v108
	v_rcp_f32_e32 v109, v109
	v_pk_mul_f32 v[18:19], v[22:23], v[18:19]
	v_mul_f32_e32 v131, 0x4b800000, v130
	v_cndmask_b32_e32 v130, v130, v131, vcc
	v_pk_mul_f32 v[98:99], v[98:99], v[108:109]
	v_rsq_f32_e32 v130, v130
	v_cvt_pk_bf16_f32 v108, v98, v99
	v_pk_mul_f32 v[98:99], v[104:105], v[186:187] op_sel_hi:[1,0]
	v_pk_mul_f32 v[20:21], v[20:21], v[132:133] op_sel_hi:[1,0]
	v_pk_mul_f32 v[102:103], v[98:99], s[30:31] op_sel_hi:[1,0]
	v_pk_mul_f32 v[98:99], v[98:99], v[100:101]
	v_exp_f32_e32 v102, v102
	v_exp_f32_e32 v103, v103
	v_mul_f32_e32 v131, 0x45800000, v130
	v_cndmask_b32_e32 v130, v130, v131, vcc
	v_pk_mul_f32 v[14:15], v[14:15], v[130:131] op_sel_hi:[1,0]
	v_pk_add_f32 v[102:103], v[102:103], 1.0 op_sel_hi:[1,0]
	v_pk_mul_f32 v[10:11], v[10:11], v[130:131] op_sel_hi:[1,0]
	v_rcp_f32_e32 v102, v102
	v_rcp_f32_e32 v103, v103
	v_pk_mul_f32 v[10:11], v[14:15], v[10:11]
	v_pk_mul_f32 v[12:13], v[12:13], v[130:131] op_sel_hi:[1,0]
	v_pk_mul_f32 v[6:7], v[6:7], v[130:131] op_sel_hi:[1,0]
	v_pk_mul_f32 v[98:99], v[98:99], v[102:103]
	v_pk_mul_f32 v[2:3], v[2:3], v[130:131] op_sel_hi:[1,0]
	v_cvt_pk_bf16_f32 v109, v98, v99
	v_lshl_add_u64 v[98:99], s[16:17], 0, v[148:149]
	v_lshl_add_u64 v[98:99], v[98:99], 0, v[0:1]
	global_store_dwordx4 v[98:99], v[106:109], off nt
	v_pk_mul_f32 v[98:99], v[94:95], s[30:31] op_sel_hi:[1,0]
	v_pk_mul_f32 v[94:95], v[96:97], v[184:185] op_sel_hi:[1,0]
	v_exp_f32_e32 v98, v98
	v_pk_mul_f32 v[96:97], v[94:95], s[30:31] op_sel_hi:[1,0]
	v_exp_f32_e32 v99, v99
	v_exp_f32_e32 v96, v96
	v_exp_f32_e32 v97, v97
	v_pk_mul_f32 v[92:93], v[94:95], v[92:93]
	v_pk_add_f32 v[98:99], v[98:99], 1.0 op_sel_hi:[1,0]
	v_pk_add_f32 v[96:97], v[96:97], 1.0 op_sel_hi:[1,0]
	v_rcp_f32_e32 v98, v98
	v_rcp_f32_e32 v99, v99
	v_rcp_f32_e32 v96, v96
	v_rcp_f32_e32 v97, v97
	v_pk_mul_f32 v[2:3], v[6:7], v[2:3]
	v_pk_mul_f32 v[90:91], v[90:91], v[98:99]
	v_pk_mul_f32 v[4:5], v[4:5], v[130:131] op_sel_hi:[1,0]
	v_pk_mul_f32 v[92:93], v[92:93], v[96:97]
	v_cvt_pk_bf16_f32 v90, v90, v91
	s_andn2_b64 vcc, exec, s[40:41]
	v_cvt_pk_bf16_f32 v91, v92, v93
	v_pk_mul_f32 v[92:93], v[86:87], s[30:31] op_sel_hi:[1,0]
	s_nop 0
	v_exp_f32_e32 v92, v92
	v_exp_f32_e32 v93, v93
	s_nop 0
	v_pk_add_f32 v[92:93], v[92:93], 1.0 op_sel_hi:[1,0]
	s_nop 0
	v_rcp_f32_e32 v92, v92
	v_rcp_f32_e32 v93, v93
	s_nop 0
	v_pk_mul_f32 v[82:83], v[82:83], v[92:93]
	s_nop 0
	v_cvt_pk_bf16_f32 v92, v82, v83
	v_pk_mul_f32 v[82:83], v[88:89], v[184:185] op_sel_hi:[1,0]
	s_nop 0
	v_pk_mul_f32 v[86:87], v[82:83], s[30:31] op_sel_hi:[1,0]
	v_pk_mul_f32 v[82:83], v[82:83], v[84:85]
	v_exp_f32_e32 v86, v86
	v_exp_f32_e32 v87, v87
	s_nop 0
	v_pk_add_f32 v[86:87], v[86:87], 1.0 op_sel_hi:[1,0]
	s_nop 0
	v_rcp_f32_e32 v86, v86
	v_rcp_f32_e32 v87, v87
	s_nop 0
	v_pk_mul_f32 v[82:83], v[82:83], v[86:87]
	s_nop 0
	v_cvt_pk_bf16_f32 v93, v82, v83
	v_lshl_add_u64 v[82:83], s[16:17], 0, v[150:151]
	v_lshl_add_u64 v[82:83], v[82:83], 0, v[0:1]
	global_store_dwordx4 v[82:83], v[90:93], off nt
	v_pk_mul_f32 v[82:83], v[78:79], s[30:31] op_sel_hi:[1,0]
	v_pk_mul_f32 v[78:79], v[80:81], v[182:183] op_sel_hi:[1,0]
	v_exp_f32_e32 v82, v82
	v_pk_mul_f32 v[80:81], v[78:79], s[30:31] op_sel_hi:[1,0]
	v_exp_f32_e32 v83, v83
	v_exp_f32_e32 v80, v80
	v_exp_f32_e32 v81, v81
	v_pk_mul_f32 v[76:77], v[78:79], v[76:77]
	v_pk_add_f32 v[82:83], v[82:83], 1.0 op_sel_hi:[1,0]
	v_pk_add_f32 v[80:81], v[80:81], 1.0 op_sel_hi:[1,0]
	v_rcp_f32_e32 v82, v82
	v_rcp_f32_e32 v83, v83
	v_rcp_f32_e32 v80, v80
	v_rcp_f32_e32 v81, v81
	v_pk_mul_f32 v[74:75], v[74:75], v[82:83]
	s_nop 0
	v_cvt_pk_bf16_f32 v74, v74, v75
	v_pk_mul_f32 v[76:77], v[76:77], v[80:81]
	s_nop 0
	v_cvt_pk_bf16_f32 v75, v76, v77
	v_pk_mul_f32 v[76:77], v[70:71], s[30:31] op_sel_hi:[1,0]
	s_nop 0
	v_exp_f32_e32 v76, v76
	v_exp_f32_e32 v77, v77
	s_nop 0
	v_pk_add_f32 v[76:77], v[76:77], 1.0 op_sel_hi:[1,0]
	s_nop 0
	v_rcp_f32_e32 v76, v76
	v_rcp_f32_e32 v77, v77
	s_nop 0
	v_pk_mul_f32 v[66:67], v[66:67], v[76:77]
	s_nop 0
	v_cvt_pk_bf16_f32 v76, v66, v67
	v_pk_mul_f32 v[66:67], v[72:73], v[182:183] op_sel_hi:[1,0]
	s_nop 0
	v_pk_mul_f32 v[70:71], v[66:67], s[30:31] op_sel_hi:[1,0]
	v_pk_mul_f32 v[66:67], v[66:67], v[68:69]
	v_exp_f32_e32 v70, v70
	v_exp_f32_e32 v71, v71
	s_nop 0
	v_pk_add_f32 v[70:71], v[70:71], 1.0 op_sel_hi:[1,0]
	s_nop 0
	v_rcp_f32_e32 v70, v70
	v_rcp_f32_e32 v71, v71
	s_nop 0
	v_pk_mul_f32 v[66:67], v[66:67], v[70:71]
	s_nop 0
	v_cvt_pk_bf16_f32 v77, v66, v67
	v_lshl_add_u64 v[66:67], s[16:17], 0, v[152:153]
	v_lshl_add_u64 v[66:67], v[66:67], 0, v[0:1]
	global_store_dwordx4 v[66:67], v[74:77], off nt
	v_pk_mul_f32 v[66:67], v[62:63], s[30:31] op_sel_hi:[1,0]
	v_pk_mul_f32 v[62:63], v[64:65], v[180:181] op_sel_hi:[1,0]
	v_exp_f32_e32 v66, v66
	v_pk_mul_f32 v[64:65], v[62:63], s[30:31] op_sel_hi:[1,0]
	v_exp_f32_e32 v67, v67
	v_exp_f32_e32 v64, v64
	v_exp_f32_e32 v65, v65
	v_pk_mul_f32 v[60:61], v[62:63], v[60:61]
	v_pk_add_f32 v[66:67], v[66:67], 1.0 op_sel_hi:[1,0]
	v_pk_add_f32 v[64:65], v[64:65], 1.0 op_sel_hi:[1,0]
	v_rcp_f32_e32 v66, v66
	v_rcp_f32_e32 v67, v67
	v_rcp_f32_e32 v64, v64
	v_rcp_f32_e32 v65, v65
	v_pk_mul_f32 v[58:59], v[58:59], v[66:67]
	s_nop 0
	v_cvt_pk_bf16_f32 v58, v58, v59
	v_pk_mul_f32 v[60:61], v[60:61], v[64:65]
	s_nop 0
	v_cvt_pk_bf16_f32 v59, v60, v61
	v_pk_mul_f32 v[60:61], v[54:55], s[30:31] op_sel_hi:[1,0]
	s_nop 0
	v_exp_f32_e32 v60, v60
	v_exp_f32_e32 v61, v61
	s_nop 0
	v_pk_add_f32 v[60:61], v[60:61], 1.0 op_sel_hi:[1,0]
	s_nop 0
	v_rcp_f32_e32 v60, v60
	v_rcp_f32_e32 v61, v61
	s_nop 0
	v_pk_mul_f32 v[50:51], v[50:51], v[60:61]
	s_nop 0
	v_cvt_pk_bf16_f32 v60, v50, v51
	v_pk_mul_f32 v[50:51], v[56:57], v[180:181] op_sel_hi:[1,0]
	s_nop 0
	v_pk_mul_f32 v[54:55], v[50:51], s[30:31] op_sel_hi:[1,0]
	v_pk_mul_f32 v[50:51], v[50:51], v[52:53]
	v_exp_f32_e32 v54, v54
	v_exp_f32_e32 v55, v55
	s_nop 0
	v_pk_add_f32 v[54:55], v[54:55], 1.0 op_sel_hi:[1,0]
	s_nop 0
	v_rcp_f32_e32 v54, v54
	v_rcp_f32_e32 v55, v55
	s_nop 0
	v_pk_mul_f32 v[50:51], v[50:51], v[54:55]
	s_nop 0
	v_cvt_pk_bf16_f32 v61, v50, v51
	v_lshl_add_u64 v[50:51], s[16:17], 0, v[154:155]
	v_lshl_add_u64 v[50:51], v[50:51], 0, v[0:1]
	global_store_dwordx4 v[50:51], v[58:61], off nt
	v_pk_mul_f32 v[50:51], v[46:47], s[30:31] op_sel_hi:[1,0]
	v_pk_mul_f32 v[46:47], v[48:49], v[178:179] op_sel_hi:[1,0]
	v_exp_f32_e32 v50, v50
	v_pk_mul_f32 v[48:49], v[46:47], s[30:31] op_sel_hi:[1,0]
	v_exp_f32_e32 v51, v51
	v_exp_f32_e32 v48, v48
	v_exp_f32_e32 v49, v49
	v_pk_mul_f32 v[44:45], v[46:47], v[44:45]
	v_pk_add_f32 v[50:51], v[50:51], 1.0 op_sel_hi:[1,0]
	v_pk_add_f32 v[48:49], v[48:49], 1.0 op_sel_hi:[1,0]
	v_rcp_f32_e32 v50, v50
	v_rcp_f32_e32 v51, v51
	v_rcp_f32_e32 v48, v48
	v_rcp_f32_e32 v49, v49
	v_pk_mul_f32 v[42:43], v[42:43], v[50:51]
	s_nop 0
	v_cvt_pk_bf16_f32 v42, v42, v43
	v_pk_mul_f32 v[44:45], v[44:45], v[48:49]
	s_nop 0
	v_cvt_pk_bf16_f32 v43, v44, v45
	v_pk_mul_f32 v[44:45], v[38:39], s[30:31] op_sel_hi:[1,0]
	s_nop 0
	v_exp_f32_e32 v44, v44
	v_exp_f32_e32 v45, v45
	s_nop 0
	v_pk_add_f32 v[44:45], v[44:45], 1.0 op_sel_hi:[1,0]
	s_nop 0
	v_rcp_f32_e32 v44, v44
	v_rcp_f32_e32 v45, v45
	s_nop 0
	v_pk_mul_f32 v[34:35], v[34:35], v[44:45]
	s_nop 0
	v_cvt_pk_bf16_f32 v44, v34, v35
	v_pk_mul_f32 v[34:35], v[40:41], v[178:179] op_sel_hi:[1,0]
	s_nop 0
	v_pk_mul_f32 v[38:39], v[34:35], s[30:31] op_sel_hi:[1,0]
	v_pk_mul_f32 v[34:35], v[34:35], v[36:37]
	v_exp_f32_e32 v38, v38
	v_exp_f32_e32 v39, v39
	s_nop 0
	v_pk_add_f32 v[38:39], v[38:39], 1.0 op_sel_hi:[1,0]
	s_nop 0
	v_rcp_f32_e32 v38, v38
	v_rcp_f32_e32 v39, v39
	s_nop 0
	v_pk_mul_f32 v[34:35], v[34:35], v[38:39]
	s_nop 0
	v_cvt_pk_bf16_f32 v45, v34, v35
	v_lshl_add_u64 v[34:35], s[16:17], 0, v[156:157]
	v_lshl_add_u64 v[34:35], v[34:35], 0, v[0:1]
	global_store_dwordx4 v[34:35], v[42:45], off nt
	v_pk_mul_f32 v[34:35], v[30:31], s[30:31] op_sel_hi:[1,0]
	v_pk_mul_f32 v[30:31], v[32:33], v[132:133] op_sel_hi:[1,0]
	v_exp_f32_e32 v34, v34
	v_pk_mul_f32 v[32:33], v[30:31], s[30:31] op_sel_hi:[1,0]
	v_exp_f32_e32 v35, v35
	v_exp_f32_e32 v32, v32
	v_exp_f32_e32 v33, v33
	v_pk_mul_f32 v[28:29], v[30:31], v[28:29]
	v_pk_add_f32 v[34:35], v[34:35], 1.0 op_sel_hi:[1,0]
	v_pk_add_f32 v[32:33], v[32:33], 1.0 op_sel_hi:[1,0]
	v_rcp_f32_e32 v34, v34
	v_rcp_f32_e32 v35, v35
	v_rcp_f32_e32 v32, v32
	v_rcp_f32_e32 v33, v33
	v_pk_mul_f32 v[26:27], v[26:27], v[34:35]
	s_nop 0
	v_cvt_pk_bf16_f32 v26, v26, v27
	v_pk_mul_f32 v[28:29], v[28:29], v[32:33]
	s_nop 0
	v_cvt_pk_bf16_f32 v27, v28, v29
	v_pk_mul_f32 v[28:29], v[22:23], s[30:31] op_sel_hi:[1,0]
	s_nop 0
	v_exp_f32_e32 v28, v28
	v_exp_f32_e32 v29, v29
	s_nop 0
	v_pk_add_f32 v[28:29], v[28:29], 1.0 op_sel_hi:[1,0]
	s_nop 0
	v_rcp_f32_e32 v28, v28
	v_rcp_f32_e32 v29, v29
	s_nop 0
	v_pk_mul_f32 v[18:19], v[18:19], v[28:29]
	s_nop 0
	v_cvt_pk_bf16_f32 v28, v18, v19
	v_pk_mul_f32 v[18:19], v[24:25], v[132:133] op_sel_hi:[1,0]
	s_nop 0
	v_pk_mul_f32 v[22:23], v[18:19], s[30:31] op_sel_hi:[1,0]
	v_pk_mul_f32 v[18:19], v[18:19], v[20:21]
	v_exp_f32_e32 v22, v22
	v_exp_f32_e32 v23, v23
	s_nop 0
	v_pk_add_f32 v[22:23], v[22:23], 1.0 op_sel_hi:[1,0]
	s_nop 0
	v_rcp_f32_e32 v22, v22
	v_rcp_f32_e32 v23, v23
	s_nop 0
	v_pk_mul_f32 v[18:19], v[18:19], v[22:23]
	s_nop 0
	v_cvt_pk_bf16_f32 v29, v18, v19
	v_lshl_add_u64 v[18:19], s[16:17], 0, v[158:159]
	v_lshl_add_u64 v[18:19], v[18:19], 0, v[0:1]
	global_store_dwordx4 v[18:19], v[26:29], off nt
	v_pk_mul_f32 v[18:19], v[14:15], s[30:31] op_sel_hi:[1,0]
	v_pk_mul_f32 v[14:15], v[16:17], v[130:131] op_sel_hi:[1,0]
	v_exp_f32_e32 v18, v18
	v_pk_mul_f32 v[16:17], v[14:15], s[30:31] op_sel_hi:[1,0]
	v_exp_f32_e32 v19, v19
	v_exp_f32_e32 v16, v16
	v_exp_f32_e32 v17, v17
	v_pk_mul_f32 v[12:13], v[14:15], v[12:13]
	v_pk_add_f32 v[18:19], v[18:19], 1.0 op_sel_hi:[1,0]
	v_pk_add_f32 v[16:17], v[16:17], 1.0 op_sel_hi:[1,0]
	v_rcp_f32_e32 v18, v18
	v_rcp_f32_e32 v19, v19
	v_rcp_f32_e32 v16, v16
	v_rcp_f32_e32 v17, v17
	v_pk_mul_f32 v[10:11], v[10:11], v[18:19]
	s_nop 0
	v_cvt_pk_bf16_f32 v10, v10, v11
	v_pk_mul_f32 v[12:13], v[12:13], v[16:17]
	s_nop 0
	v_cvt_pk_bf16_f32 v11, v12, v13
	v_pk_mul_f32 v[12:13], v[6:7], s[30:31] op_sel_hi:[1,0]
	s_nop 0
	v_exp_f32_e32 v12, v12
	v_exp_f32_e32 v13, v13
	s_nop 0
	v_pk_add_f32 v[12:13], v[12:13], 1.0 op_sel_hi:[1,0]
	s_nop 0
	v_rcp_f32_e32 v12, v12
	v_rcp_f32_e32 v13, v13
	s_nop 0
	v_pk_mul_f32 v[2:3], v[2:3], v[12:13]
	s_nop 0
	v_cvt_pk_bf16_f32 v12, v2, v3
	v_pk_mul_f32 v[2:3], v[8:9], v[130:131] op_sel_hi:[1,0]
	s_nop 0
	v_pk_mul_f32 v[6:7], v[2:3], s[30:31] op_sel_hi:[1,0]
	v_pk_mul_f32 v[2:3], v[2:3], v[4:5]
	v_exp_f32_e32 v6, v6
	v_exp_f32_e32 v7, v7
	s_nop 0
	v_pk_add_f32 v[6:7], v[6:7], 1.0 op_sel_hi:[1,0]
	s_nop 0
	v_rcp_f32_e32 v6, v6
	v_rcp_f32_e32 v7, v7
	s_nop 0
	v_pk_mul_f32 v[2:3], v[2:3], v[6:7]
	s_nop 0
	v_cvt_pk_bf16_f32 v13, v2, v3
	v_lshl_add_u64 v[2:3], s[16:17], 0, v[160:161]
	v_lshl_add_u64 v[2:3], v[2:3], 0, v[0:1]
	global_store_dwordx4 v[2:3], v[10:13], off nt
	s_mov_b64 s[16:17], -1
	s_cbranch_vccnz .LBB7_352
	s_andn2_b64 vcc, exec, s[50:51]
	s_cbranch_vccnz .LBB7_351
	s_branch .LBB7_351

.LBB7_437:
	s_waitcnt lgkmcnt(0)
	v_lshl_or_b32 v2, s10, 8, v206
	v_lshl_add_u32 v184, s89, 8, v204
	v_ashrrev_i32_e32 v3, 31, v2
	v_lshlrev_b64 v[132:133], 1, v[2:3]
	v_ashrrev_i32_e32 v185, 31, v184
	v_lshl_add_u64 v[190:191], s[68:69], 0, v[132:133]
	v_lshlrev_b64 v[134:135], 11, v[184:185]
	v_lshl_add_u64 v[136:137], v[190:191], 0, v[134:135]
	global_load_dwordx4 v[196:199], v[136:137], off
	global_load_dwordx4 v[208:211], v[136:137], off offset:256
	v_or_b32_e32 v192, 16, v184
	v_or_b32_e32 v186, 32, v184
	v_or_b32_e32 v156, 48, v184
	v_ashrrev_i32_e32 v193, 31, v192
	v_ashrrev_i32_e32 v187, 31, v186
	v_ashrrev_i32_e32 v157, 31, v156
	v_lshlrev_b64 v[194:195], 11, v[192:193]
	v_lshlrev_b64 v[188:189], 11, v[186:187]
	v_lshlrev_b64 v[158:159], 11, v[156:157]
	v_lshl_add_u64 v[134:135], s[68:69], 0, v[134:135]
	v_lshl_add_u64 v[136:137], v[190:191], 0, v[194:195]
	v_lshl_add_u64 v[138:139], v[190:191], 0, v[188:189]
	v_lshl_add_u64 v[170:171], v[190:191], 0, v[158:159]
	v_lshl_add_u64 v[172:173], v[134:135], 0, v[132:133]
	global_load_dwordx4 v[152:155], v[136:137], off
	global_load_dwordx4 v[148:151], v[136:137], off offset:256
	global_load_dwordx4 v[144:147], v[138:139], off
	global_load_dwordx4 v[140:143], v[138:139], off offset:256
	s_nop 0
	global_load_dwordx4 v[136:139], v[170:171], off
	global_load_dwordx4 v[132:135], v[170:171], off offset:256
	v_add_u32_e32 v248, 0x80, v184
	v_ashrrev_i32_e32 v249, 31, v248
	v_lshlrev_b64 v[248:249], 11, v[248:249]
	v_lshl_add_u64 v[248:249], v[190:191], 0, v[248:249]
	global_load_dwordx4 v[232:235], v[248:249], off
	global_load_dwordx4 v[236:239], v[248:249], off offset:256
	s_mov_b64 s[72:73], 0x8000
	v_lshl_add_u64 v[248:249], v[248:249], 0, s[72:73]
	global_load_dwordx4 v[240:243], v[248:249], off
	global_load_dwordx4 v[244:247], v[248:249], off offset:256
	s_lshl_b32 s16, s10, 2
	s_ashr_i32 s17, s16, 31
	s_waitcnt vmcnt(0)
	v_lshlrev_b32_e32 v212, 16, v198
	v_and_b32_e32 v213, 0xffff0000, v198
	v_lshlrev_b32_e32 v198, 16, v199
	v_and_b32_e32 v199, 0xffff0000, v199
	v_lshlrev_b32_e32 v170, 16, v196
	v_and_b32_e32 v171, 0xffff0000, v196
	v_lshlrev_b32_e32 v196, 16, v197
	v_and_b32_e32 v197, 0xffff0000, v197
	v_pk_fma_f32 v[220:221], v[126:127], 0.5, v[198:199] op_sel_hi:[1,0,1]
	v_pk_fma_f32 v[198:199], v[124:125], 0.5, v[212:213] op_sel_hi:[1,0,1]
	v_lshlrev_b32_e32 v214, 16, v208
	v_and_b32_e32 v215, 0xffff0000, v208
	v_lshlrev_b32_e32 v208, 16, v209
	v_and_b32_e32 v209, 0xffff0000, v209
	v_lshlrev_b32_e32 v216, 16, v210
	v_and_b32_e32 v217, 0xffff0000, v210
	v_lshlrev_b32_e32 v210, 16, v211
	v_and_b32_e32 v211, 0xffff0000, v211
	v_pk_fma_f32 v[218:219], v[130:131], 0.5, v[196:197] op_sel_hi:[1,0,1]
	v_pk_fma_f32 v[170:171], v[128:129], 0.5, v[170:171] op_sel_hi:[1,0,1]
	v_pk_fma_f32 v[208:209], v[98:99], 0.5, v[208:209] op_sel_hi:[1,0,1]
	v_cvt_pk_bf16_f32 v196, v170, v171
	v_cvt_pk_bf16_f32 v197, v218, v219
	v_cvt_pk_bf16_f32 v198, v198, v199
	v_cvt_pk_bf16_f32 v199, v220, v221
	v_pk_fma_f32 v[212:213], v[96:97], 0.5, v[214:215] op_sel_hi:[1,0,1]
	v_pk_fma_f32 v[214:215], v[94:95], 0.5, v[210:211] op_sel_hi:[1,0,1]
	global_store_dwordx4 v[172:173], v[196:199], off
	v_lshlrev_b32_e32 v0, 16, v196
	v_and_b32_e32 v170, 0xffff0000, v196
	v_lshlrev_b32_e32 v171, 16, v197
	v_and_b32_e32 v196, 0xffff0000, v197
	v_lshlrev_b32_e32 v197, 16, v198
	v_and_b32_e32 v198, 0xffff0000, v198
	v_lshlrev_b32_e32 v218, 16, v199
	v_and_b32_e32 v199, 0xffff0000, v199
	v_pk_fma_f32 v[216:217], v[92:93], 0.5, v[216:217] op_sel_hi:[1,0,1]
	v_cvt_pk_bf16_f32 v210, v212, v213
	v_cvt_pk_bf16_f32 v211, v208, v209
	v_mul_f32_e32 v170, v170, v170
	v_cvt_pk_bf16_f32 v212, v216, v217
	v_cvt_pk_bf16_f32 v213, v214, v215
	v_mul_f32_e32 v196, v196, v196
	v_mul_f32_e32 v198, v198, v198
	v_mul_f32_e32 v199, v199, v199
	v_and_b32_e32 v209, 0xffff0000, v210
	v_and_b32_e32 v215, 0xffff0000, v211
	v_lshlrev_b32_e32 v208, 16, v210
	v_lshlrev_b32_e32 v214, 16, v211
	v_fmac_f32_e32 v170, v0, v0
	v_fmac_f32_e32 v196, v171, v171
	v_fmac_f32_e32 v198, v197, v197
	v_fmac_f32_e32 v199, v218, v218
	v_mul_f32_e32 v0, v209, v209
	v_mul_f32_e32 v171, v215, v215
	v_and_b32_e32 v217, 0xffff0000, v212
	v_and_b32_e32 v220, 0xffff0000, v213
	v_add_f32_e32 v170, v170, v196
	v_add_f32_e32 v196, v198, v199
	v_fmac_f32_e32 v0, v208, v208
	v_fmac_f32_e32 v171, v214, v214
	v_lshlrev_b32_e32 v216, 16, v212
	v_lshlrev_b32_e32 v219, 16, v213
	v_add_f32_e32 v170, v170, v196
	v_add_f32_e32 v0, v0, v171
	v_mul_f32_e32 v171, v217, v217
	v_mul_f32_e32 v196, v220, v220
	v_fmac_f32_e32 v171, v216, v216
	v_fmac_f32_e32 v196, v219, v219
	v_add_f32_e32 v171, v171, v196
	v_add_f32_e32 v0, v0, v171
	v_and_b32_e32 v171, 64, v163
	v_add_f32_e32 v170, v170, v0
	v_xor_b32_e32 v0, 16, v163
	v_add_u32_e32 v171, 64, v171
	v_cmp_lt_i32_e32 vcc, v0, v171
	global_store_dwordx4 v[172:173], v[210:213], off offset:256
	s_nop 0
	v_cndmask_b32_e32 v0, v163, v0, vcc
	v_lshlrev_b32_e32 v0, 2, v0
	v_mov_b32_e32 v196, v170
	s_nop 1
	v_permlane16_swap_b32_e32 v170, v196
	s_waitcnt lgkmcnt(0)
	v_add_f32_e32 v196, v170, v196
	v_xor_b32_e32 v170, 32, v163
	v_cmp_lt_i32_e32 vcc, v170, v171
	s_nop 1
	v_cndmask_b32_e32 v170, v163, v170, vcc
	v_lshlrev_b32_e32 v208, 2, v170
	v_mov_b32_e32 v197, v196
	s_nop 1
	v_permlane32_swap_b32_e32 v196, v197
	s_and_saveexec_b64 s[72:73], s[40:41]
	s_cbranch_execz .LBB7_439
	v_lshlrev_b64 v[170:171], 6, v[184:185]
	v_lshl_add_u64 v[170:171], s[66:67], 0, v[170:171]
	v_lshl_add_u64 v[170:171], s[16:17], 2, v[170:171]
	s_lshl_b32 s20, s96, 2
	v_lshl_add_u64 v[170:171], v[170:171], 0, s[20:21]
	s_waitcnt lgkmcnt(0)
	v_add_f32_e32 v172, v196, v197
	global_store_dword v[170:171], v172, off
.LBB7_439:
	s_or_b64 exec, exec, s[72:73]
	v_lshlrev_b32_e32 v170, 16, v152
	v_and_b32_e32 v171, 0xffff0000, v152
	v_lshlrev_b32_e32 v152, 16, v153
	v_and_b32_e32 v153, 0xffff0000, v153
	v_lshlrev_b32_e32 v172, 16, v154
	v_and_b32_e32 v173, 0xffff0000, v154
	v_lshlrev_b32_e32 v154, 16, v155
	v_and_b32_e32 v155, 0xffff0000, v155
	s_waitcnt lgkmcnt(0)
	v_pk_fma_f32 v[196:197], v[122:123], 0.5, v[152:153] op_sel_hi:[1,0,1]
	v_pk_fma_f32 v[152:153], v[120:121], 0.5, v[170:171] op_sel_hi:[1,0,1]
	v_pk_fma_f32 v[170:171], v[118:119], 0.5, v[154:155] op_sel_hi:[1,0,1]
	v_pk_fma_f32 v[154:155], v[116:117], 0.5, v[172:173] op_sel_hi:[1,0,1]
	v_cvt_pk_bf16_f32 v152, v152, v153
	v_cvt_pk_bf16_f32 v153, v196, v197
	s_nop 0
	v_cvt_pk_bf16_f32 v154, v154, v155
	v_cvt_pk_bf16_f32 v155, v170, v171
	v_lshl_add_u64 v[170:171], s[68:69], 0, v[194:195]
	v_lshl_add_u64 v[170:171], v[2:3], 1, v[170:171]
	global_store_dwordx4 v[170:171], v[152:155], off
	v_lshlrev_b32_e32 v172, 16, v152
	v_lshlrev_b32_e32 v173, 16, v153
	v_and_b32_e32 v152, 0xffff0000, v152
	v_and_b32_e32 v153, 0xffff0000, v153
	v_mul_f32_e32 v152, v152, v152
	v_mul_f32_e32 v153, v153, v153
	v_lshlrev_b32_e32 v185, 16, v154
	v_and_b32_e32 v154, 0xffff0000, v154
	v_lshlrev_b32_e32 v194, 16, v155
	v_and_b32_e32 v155, 0xffff0000, v155
	v_fmac_f32_e32 v152, v172, v172
	v_fmac_f32_e32 v153, v173, v173
	v_add_f32_e32 v152, v152, v153
	v_mul_f32_e32 v153, v154, v154
	v_mul_f32_e32 v154, v155, v155
	v_fmac_f32_e32 v153, v185, v185
	v_fmac_f32_e32 v154, v194, v194
	v_add_f32_e32 v153, v153, v154
	v_add_f32_e32 v185, v152, v153
	v_lshlrev_b32_e32 v152, 16, v148
	v_and_b32_e32 v153, 0xffff0000, v148
	v_lshlrev_b32_e32 v148, 16, v149
	v_and_b32_e32 v149, 0xffff0000, v149
	v_lshlrev_b32_e32 v154, 16, v150
	v_and_b32_e32 v155, 0xffff0000, v150
	v_lshlrev_b32_e32 v150, 16, v151
	v_and_b32_e32 v151, 0xffff0000, v151
	v_pk_fma_f32 v[148:149], v[90:91], 0.5, v[148:149] op_sel_hi:[1,0,1]
	v_pk_fma_f32 v[152:153], v[88:89], 0.5, v[152:153] op_sel_hi:[1,0,1]
	v_pk_fma_f32 v[172:173], v[86:87], 0.5, v[150:151] op_sel_hi:[1,0,1]
	v_pk_fma_f32 v[154:155], v[84:85], 0.5, v[154:155] op_sel_hi:[1,0,1]
	v_cvt_pk_bf16_f32 v150, v152, v153
	v_cvt_pk_bf16_f32 v151, v148, v149
	s_nop 0
	v_and_b32_e32 v149, 0xffff0000, v150
	v_cvt_pk_bf16_f32 v152, v154, v155
	v_lshlrev_b32_e32 v148, 16, v150
	v_and_b32_e32 v155, 0xffff0000, v151
	v_mul_f32_e32 v149, v149, v149
	v_lshlrev_b32_e32 v154, 16, v151
	v_fmac_f32_e32 v149, v148, v148
	v_mul_f32_e32 v148, v155, v155
	v_cvt_pk_bf16_f32 v153, v172, v173
	v_and_b32_e32 v173, 0xffff0000, v152
	v_and_b32_e32 v195, 0xffff0000, v153
	v_fmac_f32_e32 v148, v154, v154
	v_lshlrev_b32_e32 v172, 16, v152
	v_lshlrev_b32_e32 v194, 16, v153
	v_add_f32_e32 v148, v149, v148
	v_mul_f32_e32 v149, v173, v173
	v_mul_f32_e32 v154, v195, v195
	v_fmac_f32_e32 v149, v172, v172
	v_fmac_f32_e32 v154, v194, v194
	v_add_f32_e32 v149, v149, v154
	v_add_f32_e32 v148, v148, v149
	v_add_f32_e32 v148, v185, v148
	v_mov_b32_e32 v149, v148
	s_nop 1
	v_permlane16_swap_b32_e32 v148, v149
	global_store_dwordx4 v[170:171], v[150:153], off offset:256
	s_waitcnt lgkmcnt(0)
	v_add_f32_e32 v148, v148, v149
	v_mov_b32_e32 v149, v148
	s_nop 1
	v_permlane32_swap_b32_e32 v148, v149
	s_and_saveexec_b64 s[72:73], s[40:41]
	s_cbranch_execz .LBB7_441
	v_lshlrev_b64 v[150:151], 6, v[192:193]
	v_lshl_add_u64 v[150:151], s[66:67], 0, v[150:151]
	v_lshl_add_u64 v[150:151], s[16:17], 2, v[150:151]
	s_lshl_b32 s20, s96, 2
	v_lshl_add_u64 v[150:151], v[150:151], 0, s[20:21]
	s_waitcnt lgkmcnt(0)
	v_add_f32_e32 v148, v148, v149
	global_store_dword v[150:151], v148, off
.LBB7_441:
	s_or_b64 exec, exec, s[72:73]
	v_lshlrev_b32_e32 v148, 16, v144
	s_waitcnt lgkmcnt(0)
	v_and_b32_e32 v149, 0xffff0000, v144
	v_lshlrev_b32_e32 v144, 16, v145
	v_and_b32_e32 v145, 0xffff0000, v145
	v_lshlrev_b32_e32 v150, 16, v146
	v_and_b32_e32 v151, 0xffff0000, v146
	v_lshlrev_b32_e32 v146, 16, v147
	v_and_b32_e32 v147, 0xffff0000, v147
	v_pk_fma_f32 v[152:153], v[114:115], 0.5, v[144:145] op_sel_hi:[1,0,1]
	v_pk_fma_f32 v[144:145], v[112:113], 0.5, v[148:149] op_sel_hi:[1,0,1]
	v_pk_fma_f32 v[148:149], v[110:111], 0.5, v[146:147] op_sel_hi:[1,0,1]
	v_pk_fma_f32 v[146:147], v[108:109], 0.5, v[150:151] op_sel_hi:[1,0,1]
	v_cvt_pk_bf16_f32 v144, v144, v145
	v_cvt_pk_bf16_f32 v145, v152, v153
	s_nop 0
	v_cvt_pk_bf16_f32 v146, v146, v147
	v_cvt_pk_bf16_f32 v147, v148, v149
	v_lshl_add_u64 v[148:149], s[68:69], 0, v[188:189]
	v_lshl_add_u64 v[148:149], v[2:3], 1, v[148:149]
	global_store_dwordx4 v[148:149], v[144:147], off
	v_lshlrev_b32_e32 v150, 16, v144
	v_lshlrev_b32_e32 v151, 16, v145
	v_and_b32_e32 v144, 0xffff0000, v144
	v_and_b32_e32 v145, 0xffff0000, v145
	v_mul_f32_e32 v144, v144, v144
	v_mul_f32_e32 v145, v145, v145
	v_lshlrev_b32_e32 v152, 16, v146
	v_and_b32_e32 v146, 0xffff0000, v146
	v_lshlrev_b32_e32 v153, 16, v147
	v_and_b32_e32 v147, 0xffff0000, v147
	v_fmac_f32_e32 v144, v150, v150
	v_fmac_f32_e32 v145, v151, v151
	v_add_f32_e32 v144, v144, v145
	v_mul_f32_e32 v145, v146, v146
	v_mul_f32_e32 v146, v147, v147
	v_fmac_f32_e32 v145, v152, v152
	v_fmac_f32_e32 v146, v153, v153
	v_add_f32_e32 v145, v145, v146
	v_add_f32_e32 v152, v144, v145
	v_lshlrev_b32_e32 v144, 16, v140
	v_and_b32_e32 v145, 0xffff0000, v140
	v_lshlrev_b32_e32 v140, 16, v141
	v_and_b32_e32 v141, 0xffff0000, v141
	v_lshlrev_b32_e32 v146, 16, v142
	v_and_b32_e32 v147, 0xffff0000, v142
	v_lshlrev_b32_e32 v142, 16, v143
	v_and_b32_e32 v143, 0xffff0000, v143
	v_pk_fma_f32 v[140:141], v[82:83], 0.5, v[140:141] op_sel_hi:[1,0,1]
	v_pk_fma_f32 v[144:145], v[80:81], 0.5, v[144:145] op_sel_hi:[1,0,1]
	v_pk_fma_f32 v[150:151], v[78:79], 0.5, v[142:143] op_sel_hi:[1,0,1]
	v_pk_fma_f32 v[146:147], v[76:77], 0.5, v[146:147] op_sel_hi:[1,0,1]
	v_cvt_pk_bf16_f32 v142, v144, v145
	v_cvt_pk_bf16_f32 v143, v140, v141
	s_nop 0
	v_and_b32_e32 v141, 0xffff0000, v142
	v_cvt_pk_bf16_f32 v144, v146, v147
	v_lshlrev_b32_e32 v140, 16, v142
	v_and_b32_e32 v147, 0xffff0000, v143
	v_mul_f32_e32 v141, v141, v141
	v_lshlrev_b32_e32 v146, 16, v143
	v_fmac_f32_e32 v141, v140, v140
	v_mul_f32_e32 v140, v147, v147
	v_cvt_pk_bf16_f32 v145, v150, v151
	v_and_b32_e32 v151, 0xffff0000, v144
	v_and_b32_e32 v154, 0xffff0000, v145
	v_fmac_f32_e32 v140, v146, v146
	v_lshlrev_b32_e32 v150, 16, v144
	v_lshlrev_b32_e32 v153, 16, v145
	v_add_f32_e32 v140, v141, v140
	v_mul_f32_e32 v141, v151, v151
	v_mul_f32_e32 v146, v154, v154
	v_fmac_f32_e32 v141, v150, v150
	v_fmac_f32_e32 v146, v153, v153
	v_add_f32_e32 v141, v141, v146
	v_add_f32_e32 v140, v140, v141
	v_add_f32_e32 v140, v152, v140
	v_mov_b32_e32 v141, v140
	s_nop 1
	v_permlane16_swap_b32_e32 v140, v141
	global_store_dwordx4 v[148:149], v[142:145], off offset:256
	s_waitcnt lgkmcnt(0)
	v_add_f32_e32 v140, v140, v141
	v_mov_b32_e32 v141, v140
	s_nop 1
	v_permlane32_swap_b32_e32 v140, v141
	s_and_saveexec_b64 s[72:73], s[40:41]
	s_cbranch_execz .LBB7_443
	v_lshlrev_b64 v[142:143], 6, v[186:187]
	v_lshl_add_u64 v[142:143], s[66:67], 0, v[142:143]
	v_lshl_add_u64 v[142:143], s[16:17], 2, v[142:143]
	s_lshl_b32 s20, s96, 2
	v_lshl_add_u64 v[142:143], v[142:143], 0, s[20:21]
	s_waitcnt lgkmcnt(0)
	v_add_f32_e32 v140, v140, v141
	global_store_dword v[142:143], v140, off
.LBB7_443:
	s_or_b64 exec, exec, s[72:73]
	v_lshlrev_b32_e32 v140, 16, v136
	s_waitcnt lgkmcnt(0)
	v_and_b32_e32 v141, 0xffff0000, v136
	v_lshlrev_b32_e32 v136, 16, v137
	v_and_b32_e32 v137, 0xffff0000, v137
	v_lshlrev_b32_e32 v142, 16, v138
	v_and_b32_e32 v143, 0xffff0000, v138
	v_lshlrev_b32_e32 v138, 16, v139
	v_and_b32_e32 v139, 0xffff0000, v139
	v_pk_fma_f32 v[144:145], v[106:107], 0.5, v[136:137] op_sel_hi:[1,0,1]
	v_pk_fma_f32 v[136:137], v[104:105], 0.5, v[140:141] op_sel_hi:[1,0,1]
	v_pk_fma_f32 v[140:141], v[102:103], 0.5, v[138:139] op_sel_hi:[1,0,1]
	v_pk_fma_f32 v[138:139], v[100:101], 0.5, v[142:143] op_sel_hi:[1,0,1]
	v_cvt_pk_bf16_f32 v136, v136, v137
	v_cvt_pk_bf16_f32 v137, v144, v145
	s_nop 0
	v_cvt_pk_bf16_f32 v138, v138, v139
	v_cvt_pk_bf16_f32 v139, v140, v141
	v_lshl_add_u64 v[140:141], s[68:69], 0, v[158:159]
	v_lshl_add_u64 v[140:141], v[2:3], 1, v[140:141]
	global_store_dwordx4 v[140:141], v[136:139], off
	v_lshlrev_b32_e32 v142, 16, v136
	v_lshlrev_b32_e32 v143, 16, v137
	v_and_b32_e32 v136, 0xffff0000, v136
	v_and_b32_e32 v137, 0xffff0000, v137
	v_mul_f32_e32 v136, v136, v136
	v_mul_f32_e32 v137, v137, v137
	v_lshlrev_b32_e32 v144, 16, v138
	v_and_b32_e32 v138, 0xffff0000, v138
	v_lshlrev_b32_e32 v145, 16, v139
	v_and_b32_e32 v139, 0xffff0000, v139
	v_fmac_f32_e32 v136, v142, v142
	v_fmac_f32_e32 v137, v143, v143
	v_add_f32_e32 v136, v136, v137
	v_mul_f32_e32 v137, v138, v138
	v_mul_f32_e32 v138, v139, v139
	v_fmac_f32_e32 v137, v144, v144
	v_fmac_f32_e32 v138, v145, v145
	v_add_f32_e32 v137, v137, v138
	v_add_f32_e32 v144, v136, v137
	v_lshlrev_b32_e32 v136, 16, v132
	v_and_b32_e32 v137, 0xffff0000, v132
	v_lshlrev_b32_e32 v132, 16, v133
	v_and_b32_e32 v133, 0xffff0000, v133
	v_lshlrev_b32_e32 v138, 16, v134
	v_and_b32_e32 v139, 0xffff0000, v134
	v_lshlrev_b32_e32 v134, 16, v135
	v_and_b32_e32 v135, 0xffff0000, v135
	v_pk_fma_f32 v[132:133], v[74:75], 0.5, v[132:133] op_sel_hi:[1,0,1]
	v_pk_fma_f32 v[136:137], v[72:73], 0.5, v[136:137] op_sel_hi:[1,0,1]
	v_pk_fma_f32 v[142:143], v[66:67], 0.5, v[134:135] op_sel_hi:[1,0,1]
	v_pk_fma_f32 v[138:139], v[64:65], 0.5, v[138:139] op_sel_hi:[1,0,1]
	v_cvt_pk_bf16_f32 v134, v136, v137
	v_cvt_pk_bf16_f32 v135, v132, v133
	s_nop 0
	v_and_b32_e32 v133, 0xffff0000, v134
	v_cvt_pk_bf16_f32 v136, v138, v139
	v_lshlrev_b32_e32 v132, 16, v134
	v_and_b32_e32 v139, 0xffff0000, v135
	v_mul_f32_e32 v133, v133, v133
	v_lshlrev_b32_e32 v138, 16, v135
	v_fmac_f32_e32 v133, v132, v132
	v_mul_f32_e32 v132, v139, v139
	v_cvt_pk_bf16_f32 v137, v142, v143
	v_and_b32_e32 v143, 0xffff0000, v136
	v_and_b32_e32 v146, 0xffff0000, v137
	v_fmac_f32_e32 v132, v138, v138
	v_lshlrev_b32_e32 v142, 16, v136
	v_lshlrev_b32_e32 v145, 16, v137
	v_add_f32_e32 v132, v133, v132
	v_mul_f32_e32 v133, v143, v143
	v_mul_f32_e32 v138, v146, v146
	v_fmac_f32_e32 v133, v142, v142
	v_fmac_f32_e32 v138, v145, v145
	v_add_f32_e32 v133, v133, v138
	v_add_f32_e32 v132, v132, v133
	v_add_f32_e32 v132, v144, v132
	v_mov_b32_e32 v133, v132
	s_nop 1
	v_permlane16_swap_b32_e32 v132, v133
	global_store_dwordx4 v[140:141], v[134:137], off offset:256
	s_waitcnt lgkmcnt(0)
	v_add_f32_e32 v132, v132, v133
	v_mov_b32_e32 v133, v132
	s_nop 1
	v_permlane32_swap_b32_e32 v132, v133
	s_and_saveexec_b64 s[72:73], s[40:41]
	s_cbranch_execz .LBB7_445
	v_lshlrev_b64 v[134:135], 6, v[156:157]
	v_lshl_add_u64 v[134:135], s[66:67], 0, v[134:135]
	v_lshl_add_u64 v[134:135], s[16:17], 2, v[134:135]
	s_lshl_b32 s20, s96, 2
	v_lshl_add_u64 v[134:135], v[134:135], 0, s[20:21]
	s_waitcnt lgkmcnt(0)
	v_add_f32_e32 v132, v132, v133
	global_store_dword v[134:135], v132, off
.LBB7_445:
	s_or_b64 exec, exec, s[72:73]
	v_add_u32_e32 v198, 0x80, v184
	v_ashrrev_i32_e32 v199, 31, v198
	v_lshlrev_b64 v[170:171], 11, v[198:199]
	s_waitcnt lgkmcnt(0)
	v_lshl_add_u64 v[132:133], v[190:191], 0, v[170:171]
	v_mov_b64_e32 v[210:211], v[232:233]
	v_mov_b64_e32 v[212:213], v[234:235]
	v_mov_b64_e32 v[156:157], v[236:237]
	v_mov_b64_e32 v[158:159], v[238:239]
	v_add_u32_e32 v194, 0x90, v184
	v_ashrrev_i32_e32 v195, 31, v194
	v_add_u32_e32 v188, 0xa0, v184
	v_lshlrev_b64 v[196:197], 11, v[194:195]
	v_ashrrev_i32_e32 v189, 31, v188
	v_add_u32_e32 v184, 0xb0, v184
	v_lshl_add_u64 v[132:133], v[190:191], 0, v[196:197]
	v_lshlrev_b64 v[192:193], 11, v[188:189]
	v_ashrrev_i32_e32 v185, 31, v184
	v_mov_b64_e32 v[152:153], v[240:241]
	v_mov_b64_e32 v[154:155], v[242:243]
	v_mov_b64_e32 v[148:149], v[244:245]
	v_mov_b64_e32 v[150:151], v[246:247]
	v_lshl_add_u64 v[132:133], v[190:191], 0, v[192:193]
	v_lshlrev_b64 v[186:187], 11, v[184:185]
	global_load_dwordx4 v[144:147], v[132:133], off
	global_load_dwordx4 v[140:143], v[132:133], off offset:256
	v_lshl_add_u64 v[132:133], v[190:191], 0, v[186:187]
	global_load_dwordx4 v[136:139], v[132:133], off
	s_nop 0
	global_load_dwordx4 v[132:135], v[132:133], off offset:256
	v_lshl_add_u64 v[170:171], s[68:69], 0, v[170:171]
	v_lshl_add_u64 v[170:171], v[2:3], 1, v[170:171]
	s_waitcnt vmcnt(7)
	v_lshlrev_b32_e32 v172, 16, v210
	v_and_b32_e32 v173, 0xffff0000, v210
	v_lshlrev_b32_e32 v190, 16, v211
	v_and_b32_e32 v191, 0xffff0000, v211
	v_lshlrev_b32_e32 v210, 16, v212
	v_and_b32_e32 v211, 0xffff0000, v212
	v_lshlrev_b32_e32 v212, 16, v213
	v_and_b32_e32 v213, 0xffff0000, v213
	v_pk_fma_f32 v[172:173], v[68:69], 0.5, v[172:173] op_sel_hi:[1,0,1]
	v_pk_fma_f32 v[190:191], v[70:71], 0.5, v[190:191] op_sel_hi:[1,0,1]
	v_pk_fma_f32 v[214:215], v[62:63], 0.5, v[212:213] op_sel_hi:[1,0,1]
	v_pk_fma_f32 v[212:213], v[60:61], 0.5, v[210:211] op_sel_hi:[1,0,1]
	v_cvt_pk_bf16_f32 v210, v172, v173
	v_cvt_pk_bf16_f32 v211, v190, v191
	s_nop 0
	v_and_b32_e32 v173, 0xffff0000, v210
	v_lshlrev_b32_e32 v172, 16, v210
	v_and_b32_e32 v191, 0xffff0000, v211
	v_mul_f32_e32 v173, v173, v173
	v_cvt_pk_bf16_f32 v212, v212, v213
	v_lshlrev_b32_e32 v190, 16, v211
	v_fmac_f32_e32 v173, v172, v172
	v_mul_f32_e32 v172, v191, v191
	v_cvt_pk_bf16_f32 v213, v214, v215
	global_store_dwordx4 v[170:171], v[210:213], off
	v_lshlrev_b32_e32 v209, 16, v212
	v_fmac_f32_e32 v172, v190, v190
	v_and_b32_e32 v210, 0xffff0000, v212
	v_and_b32_e32 v212, 0xffff0000, v213
	v_lshlrev_b32_e32 v211, 16, v213
	v_add_f32_e32 v172, v173, v172
	v_mul_f32_e32 v173, v210, v210
	v_mul_f32_e32 v190, v212, v212
	v_fmac_f32_e32 v173, v209, v209
	v_fmac_f32_e32 v190, v211, v211
	v_add_f32_e32 v173, v173, v190
	v_add_f32_e32 v209, v172, v173
	s_waitcnt vmcnt(7)
	v_lshlrev_b32_e32 v172, 16, v156
	v_and_b32_e32 v173, 0xffff0000, v156
	v_lshlrev_b32_e32 v156, 16, v157
	v_and_b32_e32 v157, 0xffff0000, v157
	v_lshlrev_b32_e32 v190, 16, v158
	v_and_b32_e32 v191, 0xffff0000, v158
	v_lshlrev_b32_e32 v158, 16, v159
	v_and_b32_e32 v159, 0xffff0000, v159
	v_pk_fma_f32 v[210:211], v[34:35], 0.5, v[156:157] op_sel_hi:[1,0,1]
	v_pk_fma_f32 v[156:157], v[32:33], 0.5, v[172:173] op_sel_hi:[1,0,1]
	v_pk_fma_f32 v[172:173], v[30:31], 0.5, v[158:159] op_sel_hi:[1,0,1]
	v_pk_fma_f32 v[158:159], v[28:29], 0.5, v[190:191] op_sel_hi:[1,0,1]
	v_cvt_pk_bf16_f32 v156, v156, v157
	v_cvt_pk_bf16_f32 v157, v210, v211
	s_nop 0
	v_cvt_pk_bf16_f32 v158, v158, v159
	v_cvt_pk_bf16_f32 v159, v172, v173
	global_store_dwordx4 v[170:171], v[156:159], off offset:256
	v_lshlrev_b32_e32 v170, 16, v156
	v_lshlrev_b32_e32 v171, 16, v157
	v_and_b32_e32 v156, 0xffff0000, v156
	v_and_b32_e32 v157, 0xffff0000, v157
	v_mul_f32_e32 v156, v156, v156
	v_mul_f32_e32 v157, v157, v157
	v_lshlrev_b32_e32 v172, 16, v158
	v_and_b32_e32 v158, 0xffff0000, v158
	v_lshlrev_b32_e32 v173, 16, v159
	v_and_b32_e32 v159, 0xffff0000, v159
	v_fmac_f32_e32 v156, v170, v170
	v_fmac_f32_e32 v157, v171, v171
	v_add_f32_e32 v156, v156, v157
	v_mul_f32_e32 v157, v158, v158
	v_mul_f32_e32 v158, v159, v159
	v_fmac_f32_e32 v157, v172, v172
	v_fmac_f32_e32 v158, v173, v173
	v_add_f32_e32 v157, v157, v158
	v_add_f32_e32 v156, v156, v157
	v_add_f32_e32 v156, v209, v156
	v_mov_b32_e32 v157, v156
	s_nop 1
	v_permlane16_swap_b32_e32 v156, v157
	s_waitcnt lgkmcnt(0)
	v_add_f32_e32 v156, v156, v157
	v_mov_b32_e32 v157, v156
	s_nop 1
	v_permlane32_swap_b32_e32 v156, v157
	s_and_saveexec_b64 s[72:73], s[40:41]
	s_cbranch_execz .LBB7_447
	v_lshlrev_b64 v[158:159], 6, v[198:199]
	v_lshl_add_u64 v[158:159], s[66:67], 0, v[158:159]
	v_lshl_add_u64 v[158:159], s[16:17], 2, v[158:159]
	s_lshl_b32 s20, s96, 2
	v_lshl_add_u64 v[158:159], v[158:159], 0, s[20:21]
	s_waitcnt lgkmcnt(0)
	v_add_f32_e32 v156, v156, v157
	global_store_dword v[158:159], v156, off
.LBB7_447:
	s_or_b64 exec, exec, s[72:73]
	s_waitcnt vmcnt(7)
	v_lshlrev_b32_e32 v156, 16, v152
	s_waitcnt lgkmcnt(0)
	v_and_b32_e32 v157, 0xffff0000, v152
	v_lshlrev_b32_e32 v152, 16, v153
	v_and_b32_e32 v153, 0xffff0000, v153
	v_lshlrev_b32_e32 v158, 16, v154
	v_and_b32_e32 v159, 0xffff0000, v154
	v_lshlrev_b32_e32 v154, 16, v155
	v_and_b32_e32 v155, 0xffff0000, v155
	v_pk_fma_f32 v[170:171], v[58:59], 0.5, v[152:153] op_sel_hi:[1,0,1]
	v_pk_fma_f32 v[152:153], v[56:57], 0.5, v[156:157] op_sel_hi:[1,0,1]
	v_pk_fma_f32 v[156:157], v[54:55], 0.5, v[154:155] op_sel_hi:[1,0,1]
	v_pk_fma_f32 v[154:155], v[52:53], 0.5, v[158:159] op_sel_hi:[1,0,1]
	v_cvt_pk_bf16_f32 v152, v152, v153
	v_cvt_pk_bf16_f32 v153, v170, v171
	s_nop 0
	v_cvt_pk_bf16_f32 v154, v154, v155
	v_cvt_pk_bf16_f32 v155, v156, v157
	v_lshl_add_u64 v[156:157], s[68:69], 0, v[196:197]
	v_lshl_add_u64 v[156:157], v[2:3], 1, v[156:157]
	global_store_dwordx4 v[156:157], v[152:155], off
	v_lshlrev_b32_e32 v158, 16, v152
	v_lshlrev_b32_e32 v159, 16, v153
	v_and_b32_e32 v152, 0xffff0000, v152
	v_and_b32_e32 v153, 0xffff0000, v153
	v_mul_f32_e32 v152, v152, v152
	v_mul_f32_e32 v153, v153, v153
	v_lshlrev_b32_e32 v170, 16, v154
	v_and_b32_e32 v154, 0xffff0000, v154
	v_lshlrev_b32_e32 v171, 16, v155
	v_and_b32_e32 v155, 0xffff0000, v155
	v_fmac_f32_e32 v152, v158, v158
	v_fmac_f32_e32 v153, v159, v159
	v_add_f32_e32 v152, v152, v153
	v_mul_f32_e32 v153, v154, v154
	v_mul_f32_e32 v154, v155, v155
	v_fmac_f32_e32 v153, v170, v170
	v_fmac_f32_e32 v154, v171, v171
	v_add_f32_e32 v153, v153, v154
	v_add_f32_e32 v170, v152, v153
	s_waitcnt vmcnt(7)
	v_lshlrev_b32_e32 v152, 16, v148
	v_and_b32_e32 v153, 0xffff0000, v148
	v_lshlrev_b32_e32 v148, 16, v149
	v_and_b32_e32 v149, 0xffff0000, v149
	v_lshlrev_b32_e32 v154, 16, v150
	v_and_b32_e32 v155, 0xffff0000, v150
	v_lshlrev_b32_e32 v150, 16, v151
	v_and_b32_e32 v151, 0xffff0000, v151
	v_pk_fma_f32 v[148:149], v[26:27], 0.5, v[148:149] op_sel_hi:[1,0,1]
	v_pk_fma_f32 v[152:153], v[24:25], 0.5, v[152:153] op_sel_hi:[1,0,1]
	v_pk_fma_f32 v[158:159], v[22:23], 0.5, v[150:151] op_sel_hi:[1,0,1]
	v_pk_fma_f32 v[154:155], v[20:21], 0.5, v[154:155] op_sel_hi:[1,0,1]
	v_cvt_pk_bf16_f32 v150, v152, v153
	v_cvt_pk_bf16_f32 v151, v148, v149
	s_nop 0
	v_and_b32_e32 v149, 0xffff0000, v150
	v_cvt_pk_bf16_f32 v152, v154, v155
	v_lshlrev_b32_e32 v148, 16, v150
	v_and_b32_e32 v155, 0xffff0000, v151
	v_mul_f32_e32 v149, v149, v149
	v_lshlrev_b32_e32 v154, 16, v151
	v_fmac_f32_e32 v149, v148, v148
	v_mul_f32_e32 v148, v155, v155
	v_cvt_pk_bf16_f32 v153, v158, v159
	v_and_b32_e32 v159, 0xffff0000, v152
	v_and_b32_e32 v172, 0xffff0000, v153
	v_fmac_f32_e32 v148, v154, v154
	v_lshlrev_b32_e32 v158, 16, v152
	v_lshlrev_b32_e32 v171, 16, v153
	v_add_f32_e32 v148, v149, v148
	v_mul_f32_e32 v149, v159, v159
	v_mul_f32_e32 v154, v172, v172
	v_fmac_f32_e32 v149, v158, v158
	v_fmac_f32_e32 v154, v171, v171
	v_add_f32_e32 v149, v149, v154
	v_add_f32_e32 v148, v148, v149
	v_add_f32_e32 v148, v170, v148
	v_mov_b32_e32 v149, v148
	s_nop 1
	v_permlane16_swap_b32_e32 v148, v149
	global_store_dwordx4 v[156:157], v[150:153], off offset:256
	s_waitcnt lgkmcnt(0)
	v_add_f32_e32 v148, v148, v149
	v_mov_b32_e32 v149, v148
	s_nop 1
	v_permlane32_swap_b32_e32 v148, v149
	s_and_saveexec_b64 s[72:73], s[40:41]
	s_cbranch_execz .LBB7_449
	v_lshlrev_b64 v[150:151], 6, v[194:195]
	v_lshl_add_u64 v[150:151], s[66:67], 0, v[150:151]
	v_lshl_add_u64 v[150:151], s[16:17], 2, v[150:151]
	s_lshl_b32 s20, s96, 2
	v_lshl_add_u64 v[150:151], v[150:151], 0, s[20:21]
	s_waitcnt lgkmcnt(0)
	v_add_f32_e32 v148, v148, v149
	global_store_dword v[150:151], v148, off
.LBB7_449:
	s_or_b64 exec, exec, s[72:73]
	s_waitcnt vmcnt(7)
	v_lshlrev_b32_e32 v148, 16, v144
	s_waitcnt lgkmcnt(0)
	v_and_b32_e32 v149, 0xffff0000, v144
	v_lshlrev_b32_e32 v144, 16, v145
	v_and_b32_e32 v145, 0xffff0000, v145
	v_lshlrev_b32_e32 v150, 16, v146
	v_and_b32_e32 v151, 0xffff0000, v146
	v_lshlrev_b32_e32 v146, 16, v147
	v_and_b32_e32 v147, 0xffff0000, v147
	v_pk_fma_f32 v[152:153], v[50:51], 0.5, v[144:145] op_sel_hi:[1,0,1]
	v_pk_fma_f32 v[144:145], v[48:49], 0.5, v[148:149] op_sel_hi:[1,0,1]
	v_pk_fma_f32 v[148:149], v[46:47], 0.5, v[146:147] op_sel_hi:[1,0,1]
	v_pk_fma_f32 v[146:147], v[44:45], 0.5, v[150:151] op_sel_hi:[1,0,1]
	v_cvt_pk_bf16_f32 v144, v144, v145
	v_cvt_pk_bf16_f32 v145, v152, v153
	s_nop 0
	v_cvt_pk_bf16_f32 v146, v146, v147
	v_cvt_pk_bf16_f32 v147, v148, v149
	v_lshl_add_u64 v[148:149], s[68:69], 0, v[192:193]
	v_lshl_add_u64 v[148:149], v[2:3], 1, v[148:149]
	global_store_dwordx4 v[148:149], v[144:147], off
	v_lshlrev_b32_e32 v150, 16, v144
	v_lshlrev_b32_e32 v151, 16, v145
	v_and_b32_e32 v144, 0xffff0000, v144
	v_and_b32_e32 v145, 0xffff0000, v145
	v_mul_f32_e32 v144, v144, v144
	v_mul_f32_e32 v145, v145, v145
	v_lshlrev_b32_e32 v152, 16, v146
	v_and_b32_e32 v146, 0xffff0000, v146
	v_lshlrev_b32_e32 v153, 16, v147
	v_and_b32_e32 v147, 0xffff0000, v147
	v_fmac_f32_e32 v144, v150, v150
	v_fmac_f32_e32 v145, v151, v151
	v_add_f32_e32 v144, v144, v145
	v_mul_f32_e32 v145, v146, v146
	v_mul_f32_e32 v146, v147, v147
	v_fmac_f32_e32 v145, v152, v152
	v_fmac_f32_e32 v146, v153, v153
	v_add_f32_e32 v145, v145, v146
	v_add_f32_e32 v152, v144, v145
	s_waitcnt vmcnt(7)
	v_lshlrev_b32_e32 v144, 16, v140
	v_and_b32_e32 v145, 0xffff0000, v140
	v_lshlrev_b32_e32 v140, 16, v141
	v_and_b32_e32 v141, 0xffff0000, v141
	v_lshlrev_b32_e32 v146, 16, v142
	v_and_b32_e32 v147, 0xffff0000, v142
	v_lshlrev_b32_e32 v142, 16, v143
	v_and_b32_e32 v143, 0xffff0000, v143
	v_pk_fma_f32 v[140:141], v[18:19], 0.5, v[140:141] op_sel_hi:[1,0,1]
	v_pk_fma_f32 v[144:145], v[16:17], 0.5, v[144:145] op_sel_hi:[1,0,1]
	v_pk_fma_f32 v[150:151], v[14:15], 0.5, v[142:143] op_sel_hi:[1,0,1]
	v_pk_fma_f32 v[146:147], v[12:13], 0.5, v[146:147] op_sel_hi:[1,0,1]
	v_cvt_pk_bf16_f32 v142, v144, v145
	v_cvt_pk_bf16_f32 v143, v140, v141
	s_nop 0
	v_and_b32_e32 v141, 0xffff0000, v142
	v_cvt_pk_bf16_f32 v144, v146, v147
	v_lshlrev_b32_e32 v140, 16, v142
	v_and_b32_e32 v147, 0xffff0000, v143
	v_mul_f32_e32 v141, v141, v141
	v_lshlrev_b32_e32 v146, 16, v143
	v_fmac_f32_e32 v141, v140, v140
	v_mul_f32_e32 v140, v147, v147
	v_cvt_pk_bf16_f32 v145, v150, v151
	v_and_b32_e32 v151, 0xffff0000, v144
	v_and_b32_e32 v154, 0xffff0000, v145
	v_fmac_f32_e32 v140, v146, v146
	v_lshlrev_b32_e32 v150, 16, v144
	v_lshlrev_b32_e32 v153, 16, v145
	v_add_f32_e32 v140, v141, v140
	v_mul_f32_e32 v141, v151, v151
	v_mul_f32_e32 v146, v154, v154
	v_fmac_f32_e32 v141, v150, v150
	v_fmac_f32_e32 v146, v153, v153
	v_add_f32_e32 v141, v141, v146
	v_add_f32_e32 v140, v140, v141
	v_add_f32_e32 v140, v152, v140
	v_mov_b32_e32 v141, v140
	s_nop 1
	v_permlane16_swap_b32_e32 v140, v141
	global_store_dwordx4 v[148:149], v[142:145], off offset:256
	s_waitcnt lgkmcnt(0)
	v_add_f32_e32 v140, v140, v141
	v_mov_b32_e32 v141, v140
	s_nop 1
	v_permlane32_swap_b32_e32 v140, v141
	s_and_saveexec_b64 s[72:73], s[40:41]
	s_cbranch_execz .LBB7_451
	v_lshlrev_b64 v[142:143], 6, v[188:189]
	v_lshl_add_u64 v[142:143], s[66:67], 0, v[142:143]
	v_lshl_add_u64 v[142:143], s[16:17], 2, v[142:143]
	s_lshl_b32 s20, s96, 2
	v_lshl_add_u64 v[142:143], v[142:143], 0, s[20:21]
	s_waitcnt lgkmcnt(0)
	v_add_f32_e32 v140, v140, v141
	global_store_dword v[142:143], v140, off
.LBB7_451:
	s_or_b64 exec, exec, s[72:73]
	s_waitcnt vmcnt(7)
	v_lshlrev_b32_e32 v140, 16, v136
	s_waitcnt lgkmcnt(0)
	v_and_b32_e32 v141, 0xffff0000, v136
	v_lshlrev_b32_e32 v136, 16, v137
	v_and_b32_e32 v137, 0xffff0000, v137
	v_lshlrev_b32_e32 v142, 16, v138
	v_and_b32_e32 v143, 0xffff0000, v138
	v_lshlrev_b32_e32 v138, 16, v139
	v_and_b32_e32 v139, 0xffff0000, v139
	v_pk_fma_f32 v[144:145], v[42:43], 0.5, v[136:137] op_sel_hi:[1,0,1]
	v_pk_fma_f32 v[136:137], v[40:41], 0.5, v[140:141] op_sel_hi:[1,0,1]
	v_pk_fma_f32 v[140:141], v[38:39], 0.5, v[138:139] op_sel_hi:[1,0,1]
	v_pk_fma_f32 v[138:139], v[36:37], 0.5, v[142:143] op_sel_hi:[1,0,1]
	v_cvt_pk_bf16_f32 v136, v136, v137
	v_cvt_pk_bf16_f32 v137, v144, v145
	s_nop 0
	v_cvt_pk_bf16_f32 v138, v138, v139
	v_cvt_pk_bf16_f32 v139, v140, v141
	v_lshl_add_u64 v[140:141], s[68:69], 0, v[186:187]
	v_lshl_add_u64 v[140:141], v[2:3], 1, v[140:141]
	v_and_b32_e32 v3, 0xffff0000, v136
	global_store_dwordx4 v[140:141], v[136:139], off
	v_lshlrev_b32_e32 v2, 16, v136
	v_mul_f32_e32 v3, v3, v3
	v_lshlrev_b32_e32 v136, 16, v137
	v_and_b32_e32 v137, 0xffff0000, v137
	v_fmac_f32_e32 v3, v2, v2
	v_mul_f32_e32 v2, v137, v137
	v_lshlrev_b32_e32 v142, 16, v138
	v_and_b32_e32 v138, 0xffff0000, v138
	v_lshlrev_b32_e32 v143, 16, v139
	v_and_b32_e32 v139, 0xffff0000, v139
	v_fmac_f32_e32 v2, v136, v136
	v_add_f32_e32 v2, v3, v2
	v_mul_f32_e32 v3, v138, v138
	v_mul_f32_e32 v136, v139, v139
	v_fmac_f32_e32 v3, v142, v142
	v_fmac_f32_e32 v136, v143, v143
	v_add_f32_e32 v3, v3, v136
	v_add_f32_e32 v144, v2, v3
	s_waitcnt vmcnt(7)
	v_lshlrev_b32_e32 v2, 16, v132
	v_and_b32_e32 v3, 0xffff0000, v132
	v_lshlrev_b32_e32 v132, 16, v133
	v_and_b32_e32 v133, 0xffff0000, v133
	v_pk_fma_f32 v[2:3], v[8:9], 0.5, v[2:3] op_sel_hi:[1,0,1]
	v_lshlrev_b32_e32 v136, 16, v134
	v_and_b32_e32 v137, 0xffff0000, v134
	v_lshlrev_b32_e32 v134, 16, v135
	v_and_b32_e32 v135, 0xffff0000, v135
	v_pk_fma_f32 v[138:139], v[10:11], 0.5, v[132:133] op_sel_hi:[1,0,1]
	v_cvt_pk_bf16_f32 v132, v2, v3
	v_pk_fma_f32 v[142:143], v[6:7], 0.5, v[134:135] op_sel_hi:[1,0,1]
	v_and_b32_e32 v3, 0xffff0000, v132
	v_pk_fma_f32 v[134:135], v[4:5], 0.5, v[136:137] op_sel_hi:[1,0,1]
	v_cvt_pk_bf16_f32 v133, v138, v139
	v_lshlrev_b32_e32 v2, 16, v132
	v_and_b32_e32 v137, 0xffff0000, v133
	v_mul_f32_e32 v3, v3, v3
	v_lshlrev_b32_e32 v136, 16, v133
	v_fmac_f32_e32 v3, v2, v2
	v_mul_f32_e32 v2, v137, v137
	v_cvt_pk_bf16_f32 v134, v134, v135
	v_cvt_pk_bf16_f32 v135, v142, v143
	v_fmac_f32_e32 v2, v136, v136
	v_and_b32_e32 v139, 0xffff0000, v134
	v_and_b32_e32 v143, 0xffff0000, v135
	v_lshlrev_b32_e32 v138, 16, v134
	v_lshlrev_b32_e32 v142, 16, v135
	v_add_f32_e32 v2, v3, v2
	v_mul_f32_e32 v3, v139, v139
	v_mul_f32_e32 v136, v143, v143
	v_fmac_f32_e32 v3, v138, v138
	v_fmac_f32_e32 v136, v142, v142
	v_add_f32_e32 v3, v3, v136
	v_add_f32_e32 v2, v2, v3
	v_add_f32_e32 v2, v144, v2
	v_mov_b32_e32 v0, v2
	s_nop 1
	v_permlane16_swap_b32_e32 v2, v0
	global_store_dwordx4 v[140:141], v[132:135], off offset:256
	s_waitcnt lgkmcnt(0)
	v_add_f32_e32 v0, v2, v0
	v_mov_b32_e32 v2, v0
	s_nop 1
	v_permlane32_swap_b32_e32 v0, v2
	s_and_saveexec_b64 s[72:73], s[40:41]
	s_cbranch_execz .LBB7_453
	v_lshlrev_b64 v[132:133], 6, v[184:185]
	v_lshl_add_u64 v[132:133], s[66:67], 0, v[132:133]
	v_lshl_add_u64 v[132:133], s[16:17], 2, v[132:133]
	s_lshl_b32 s20, s96, 2
	v_lshl_add_u64 v[132:133], v[132:133], 0, s[20:21]
	s_waitcnt lgkmcnt(0)
	v_add_f32_e32 v0, v0, v2
	global_store_dword v[132:133], v0, off

.LBB7_526:
	v_lshl_add_u32 v192, s28, 8, v143
	v_ashrrev_i32_e32 v193, 31, v192
	v_lshlrev_b64 v[192:193], 6, v[192:193]
	v_lshl_add_u64 v[192:193], v[144:145], 0, v[192:193]
	global_load_dwordx4 v[204:207], v[192:193], off offset:1024
	global_load_dwordx4 v[208:211], v[192:193], off offset:2048
	global_load_dwordx4 v[212:215], v[192:193], off offset:3072
	v_add_co_u32_e32 v192, vcc, 0x2000, v192
	s_nop 1
	v_addc_co_u32_e32 v193, vcc, 0, v193, vcc
	global_load_dwordx4 v[216:219], v[192:193], off
	global_load_dwordx4 v[220:223], v[192:193], off offset:1024
	global_load_dwordx4 v[224:227], v[192:193], off offset:2048
	global_load_dwordx4 v[228:231], v[192:193], off offset:3072
	v_and_b32_e32 v130, 64, v163
	v_xor_b32_e32 v0, 16, v163
	v_add_u32_e32 v130, 64, v130
	v_cmp_lt_i32_e32 vcc, v0, v130
	v_lshl_add_u32 v184, s28, 8, v143
	v_ashrrev_i32_e32 v185, 31, v184
	v_cndmask_b32_e32 v0, v163, v0, vcc
	v_lshlrev_b32_e32 v191, 2, v0
	v_xor_b32_e32 v0, 32, v163
	v_cmp_lt_i32_e32 vcc, v0, v130
	v_lshlrev_b64 v[130:131], 6, v[184:185]
	v_lshl_add_u64 v[130:131], v[144:145], 0, v[130:131]
	global_load_dwordx4 v[130:133], v[130:131], off
	v_or_b32_e32 v180, 16, v184
	v_ashrrev_i32_e32 v181, 31, v180
	v_cndmask_b32_e32 v0, v163, v0, vcc
	v_lshlrev_b32_e32 v0, 2, v0
	v_or_b32_e32 v178, 32, v184
	v_ashrrev_i32_e32 v179, 31, v178
	v_or_b32_e32 v158, 48, v184
	v_ashrrev_i32_e32 v159, 31, v158
	v_add_u32_e32 v156, 0x80, v184
	v_ashrrev_i32_e32 v157, 31, v156
	v_add_u32_e32 v154, 0x90, v184
	v_ashrrev_i32_e32 v155, 31, v154
	s_lshl_b32 s13, s10, 8
	s_or_b32 s10, s13, s31
	s_movk_i32 s15, 0x17f
	v_lshlrev_b64 v[192:193], 11, v[184:185]
	s_waitcnt vmcnt(0)
	v_mov_b32_e32 v150, v131
	v_mov_b32_e32 v151, v132
	v_mov_b32_e32 v131, v133
	v_pk_add_f32 v[150:151], v[150:151], v[130:131]
	v_lshlrev_b64 v[130:131], 6, v[180:181]
	v_lshl_add_u64 v[130:131], v[144:145], 0, v[130:131]
	v_mov_b64_e32 v[130:131], v[204:205]
	v_mov_b64_e32 v[132:133], v[206:207]
	v_mov_b32_e32 v152, v131
	v_mov_b32_e32 v153, v132
	v_mov_b32_e32 v131, v133
	v_pk_add_f32 v[130:131], v[152:153], v[130:131]
	v_mov_b32_e32 v133, v150
	v_mov_b32_e32 v132, v130
	v_mov_b32_e32 v150, v131
	v_pk_add_f32 v[130:131], v[132:133], v[150:151]
	v_mov_b32_e32 v133, v131
	s_nop 1
	v_permlane16_swap_b32_e32 v131, v133
	v_mov_b32_e32 v132, v130
	s_nop 1
	v_permlane16_swap_b32_e32 v130, v132
	s_waitcnt lgkmcnt(0)
	v_pk_add_f32 v[130:131], v[130:131], v[132:133]
	v_mov_b32_e32 v133, v131
	s_nop 1
	v_permlane32_swap_b32_e32 v131, v133
	v_mov_b32_e32 v132, v130
	s_nop 1
	v_permlane32_swap_b32_e32 v130, v132
	s_waitcnt lgkmcnt(0)
	v_pk_add_f32 v[130:131], v[130:131], v[132:133]
	s_nop 0
	v_pk_fma_f32 v[188:189], v[130:131], s[26:27], v[162:163] op_sel_hi:[1,0,0]
	s_nop 0
	v_mul_f32_e32 v130, 0x4b800000, v189
	v_cmp_gt_f32_e32 vcc, s11, v189
	v_cmp_gt_f32_e64 s[44:45], s11, v188
	s_nop 0
	v_cndmask_b32_e32 v130, v189, v130, vcc
	v_rsq_f32_e32 v130, v130
	s_nop 0
	v_mul_f32_e32 v131, 0x45800000, v130
	v_cndmask_b32_e32 v190, v130, v131, vcc
	v_lshlrev_b64 v[130:131], 6, v[178:179]
	v_lshl_add_u64 v[130:131], v[144:145], 0, v[130:131]
	v_pk_mul_f32 v[128:129], v[128:129], v[190:191] op_sel_hi:[1,0]
	v_pk_mul_f32 v[126:127], v[126:127], v[190:191] op_sel_hi:[1,0]
	v_mov_b64_e32 v[130:131], v[208:209]
	v_mov_b64_e32 v[132:133], v[210:211]
	v_mov_b32_e32 v150, v131
	v_mov_b32_e32 v151, v132
	v_mov_b32_e32 v131, v133
	v_pk_add_f32 v[150:151], v[150:151], v[130:131]
	v_lshlrev_b64 v[130:131], 6, v[158:159]
	v_lshl_add_u64 v[130:131], v[144:145], 0, v[130:131]
	v_mov_b64_e32 v[130:131], v[212:213]
	v_mov_b64_e32 v[132:133], v[214:215]
	v_mov_b32_e32 v152, v131
	v_mov_b32_e32 v153, v132
	v_mov_b32_e32 v131, v133
	v_pk_add_f32 v[130:131], v[152:153], v[130:131]
	v_mov_b32_e32 v133, v150
	v_mov_b32_e32 v132, v130
	v_mov_b32_e32 v150, v131
	v_pk_add_f32 v[130:131], v[132:133], v[150:151]
	v_mov_b32_e32 v133, v131
	s_nop 1
	v_permlane16_swap_b32_e32 v131, v133
	v_mov_b32_e32 v132, v130
	s_nop 1
	v_permlane16_swap_b32_e32 v130, v132
	s_waitcnt lgkmcnt(0)
	v_pk_add_f32 v[182:183], v[130:131], v[132:133]
	v_lshlrev_b64 v[130:131], 6, v[156:157]
	v_lshl_add_u64 v[130:131], v[144:145], 0, v[130:131]
	ds_bpermute_b32 v187, v0, v183
	ds_bpermute_b32 v186, v0, v182
	v_mov_b64_e32 v[130:131], v[216:217]
	v_mov_b64_e32 v[132:133], v[218:219]
	v_mov_b32_e32 v150, v131
	v_mov_b32_e32 v151, v132
	v_mov_b32_e32 v131, v133
	v_pk_add_f32 v[150:151], v[150:151], v[130:131]
	v_lshlrev_b64 v[130:131], 6, v[154:155]
	v_lshl_add_u64 v[130:131], v[144:145], 0, v[130:131]
	v_mov_b64_e32 v[130:131], v[220:221]
	v_mov_b64_e32 v[132:133], v[222:223]
	v_mov_b32_e32 v152, v131
	v_mov_b32_e32 v153, v132
	v_mov_b32_e32 v131, v133
	v_pk_add_f32 v[130:131], v[152:153], v[130:131]
	v_mov_b32_e32 v133, v150
	v_mov_b32_e32 v132, v130
	v_mov_b32_e32 v150, v131
	v_pk_add_f32 v[130:131], v[132:133], v[150:151]
	v_mov_b32_e32 v133, v131
	s_nop 1
	v_permlane16_swap_b32_e32 v131, v133
	v_mov_b32_e32 v132, v130
	s_nop 1
	v_permlane16_swap_b32_e32 v130, v132
	v_add_u32_e32 v152, 0xa0, v184
	v_ashrrev_i32_e32 v153, 31, v152
	s_waitcnt lgkmcnt(0)
	v_pk_add_f32 v[160:161], v[130:131], v[132:133]
	v_lshlrev_b64 v[130:131], 6, v[152:153]
	v_lshl_add_u64 v[130:131], v[144:145], 0, v[130:131]
	ds_bpermute_b32 v175, v0, v161
	ds_bpermute_b32 v174, v0, v160
	v_mov_b64_e32 v[130:131], v[224:225]
	v_mov_b64_e32 v[132:133], v[226:227]
	v_mov_b32_e32 v150, v131
	v_mov_b32_e32 v151, v132
	v_mov_b32_e32 v131, v133
	v_pk_add_f32 v[176:177], v[150:151], v[130:131]
	v_add_u32_e32 v150, 0xb0, v184
	v_ashrrev_i32_e32 v151, 31, v150
	v_lshlrev_b64 v[130:131], 6, v[150:151]
	v_lshl_add_u64 v[130:131], v[144:145], 0, v[130:131]
	v_mov_b64_e32 v[130:131], v[228:229]
	v_mov_b64_e32 v[132:133], v[230:231]
	v_mov_b32_e32 v170, v131
	v_mov_b32_e32 v171, v132
	v_mov_b32_e32 v131, v133
	v_pk_add_f32 v[130:131], v[170:171], v[130:131]
	v_mov_b32_e32 v133, v176
	v_mov_b32_e32 v132, v130
	v_mov_b32_e32 v176, v131
	v_pk_add_f32 v[130:131], v[132:133], v[176:177]
	v_mov_b32_e32 v133, v131
	s_nop 1
	v_permlane16_swap_b32_e32 v131, v133
	v_mov_b32_e32 v132, v130
	s_nop 1
	v_permlane16_swap_b32_e32 v130, v132
	v_pk_mul_f32 v[170:171], v[124:125], v[190:191] op_sel_hi:[1,0]
	v_pk_mul_f32 v[124:125], v[122:123], v[190:191] op_sel_hi:[1,0]
	v_cvt_pk_bf16_f32 v122, v126, v127
	v_cvt_pk_bf16_f32 v123, v128, v129
	s_waitcnt lgkmcnt(0)
	v_pk_add_f32 v[132:133], v[130:131], v[132:133]
	ds_bpermute_b32 v177, v0, v133
	ds_bpermute_b32 v176, v0, v132
	v_or_b32_e32 v130, s10, v194
	v_cmp_lt_i32_e64 s[42:43], s15, v130
	v_cvt_pk_bf16_f32 v124, v124, v125
	v_cvt_pk_bf16_f32 v125, v170, v171
	s_and_saveexec_b64 s[16:17], s[42:43]
	s_xor_b64 s[16:17], exec, s[16:17]
	s_cbranch_execz .LBB7_529
	s_cmpk_gt_u32 s13, 0x57f
	s_cbranch_scc1 .LBB7_529
	v_lshl_add_u64 v[126:127], s[94:95], 0, v[192:193]
	v_mov_b32_e32 v131, v1
	v_lshl_add_u64 v[126:127], v[130:131], 1, v[126:127]
	global_store_dwordx4 v[126:127], v[122:125], off offset:-768

.LBB7_1107:
	s_waitcnt lgkmcnt(0)
	v_lshl_or_b32 v2, s57, 8, v206
	v_lshl_add_u32 v184, s88, 8, v204
	v_ashrrev_i32_e32 v3, 31, v2
	v_lshlrev_b64 v[132:133], 1, v[2:3]
	v_ashrrev_i32_e32 v185, 31, v184
	v_lshl_add_u64 v[190:191], s[68:69], 0, v[132:133]
	v_lshlrev_b64 v[134:135], 11, v[184:185]
	v_lshl_add_u64 v[136:137], v[190:191], 0, v[134:135]
	global_load_dwordx4 v[196:199], v[136:137], off
	global_load_dwordx4 v[208:211], v[136:137], off offset:256
	v_or_b32_e32 v192, 16, v184
	v_or_b32_e32 v186, 32, v184
	v_or_b32_e32 v156, 48, v184
	v_ashrrev_i32_e32 v193, 31, v192
	v_ashrrev_i32_e32 v187, 31, v186
	v_ashrrev_i32_e32 v157, 31, v156
	v_lshlrev_b64 v[194:195], 11, v[192:193]
	v_lshlrev_b64 v[188:189], 11, v[186:187]
	v_lshlrev_b64 v[158:159], 11, v[156:157]
	v_lshl_add_u64 v[134:135], s[68:69], 0, v[134:135]
	v_lshl_add_u64 v[136:137], v[190:191], 0, v[194:195]
	v_lshl_add_u64 v[138:139], v[190:191], 0, v[188:189]
	v_lshl_add_u64 v[170:171], v[190:191], 0, v[158:159]
	v_lshl_add_u64 v[172:173], v[134:135], 0, v[132:133]
	global_load_dwordx4 v[152:155], v[136:137], off
	global_load_dwordx4 v[148:151], v[136:137], off offset:256
	global_load_dwordx4 v[144:147], v[138:139], off
	global_load_dwordx4 v[140:143], v[138:139], off offset:256
	s_nop 0
	global_load_dwordx4 v[136:139], v[170:171], off
	global_load_dwordx4 v[132:135], v[170:171], off offset:256
	v_add_u32_e32 v248, 0x80, v184
	v_ashrrev_i32_e32 v249, 31, v248
	v_lshlrev_b64 v[248:249], 11, v[248:249]
	v_lshl_add_u64 v[248:249], v[190:191], 0, v[248:249]
	global_load_dwordx4 v[232:235], v[248:249], off
	global_load_dwordx4 v[236:239], v[248:249], off offset:256
	s_mov_b64 s[72:73], 0x8000
	v_lshl_add_u64 v[248:249], v[248:249], 0, s[72:73]
	global_load_dwordx4 v[240:243], v[248:249], off
	global_load_dwordx4 v[244:247], v[248:249], off offset:256
	s_waitcnt vmcnt(0)
	v_lshlrev_b32_e32 v212, 16, v198
	v_and_b32_e32 v213, 0xffff0000, v198
	v_lshlrev_b32_e32 v198, 16, v199
	v_and_b32_e32 v199, 0xffff0000, v199
	v_lshlrev_b32_e32 v170, 16, v196
	v_and_b32_e32 v171, 0xffff0000, v196
	v_lshlrev_b32_e32 v196, 16, v197
	v_and_b32_e32 v197, 0xffff0000, v197
	v_pk_add_f32 v[220:221], v[126:127], v[198:199]
	v_pk_add_f32 v[198:199], v[124:125], v[212:213]
	v_lshlrev_b32_e32 v214, 16, v208
	v_and_b32_e32 v215, 0xffff0000, v208
	v_lshlrev_b32_e32 v208, 16, v209
	v_and_b32_e32 v209, 0xffff0000, v209
	v_lshlrev_b32_e32 v216, 16, v210
	v_and_b32_e32 v217, 0xffff0000, v210
	v_lshlrev_b32_e32 v210, 16, v211
	v_and_b32_e32 v211, 0xffff0000, v211
	v_pk_add_f32 v[218:219], v[130:131], v[196:197]
	v_pk_add_f32 v[170:171], v[128:129], v[170:171]
	v_pk_add_f32 v[208:209], v[98:99], v[208:209]
	v_cvt_pk_bf16_f32 v196, v170, v171
	v_cvt_pk_bf16_f32 v197, v218, v219
	v_cvt_pk_bf16_f32 v198, v198, v199
	v_cvt_pk_bf16_f32 v199, v220, v221
	v_pk_add_f32 v[212:213], v[96:97], v[214:215]
	v_pk_add_f32 v[214:215], v[94:95], v[210:211]
	global_store_dwordx4 v[172:173], v[196:199], off
	v_lshlrev_b32_e32 v0, 16, v196
	v_and_b32_e32 v170, 0xffff0000, v196
	v_lshlrev_b32_e32 v171, 16, v197
	v_and_b32_e32 v196, 0xffff0000, v197
	v_lshlrev_b32_e32 v197, 16, v198
	v_and_b32_e32 v198, 0xffff0000, v198
	v_lshlrev_b32_e32 v218, 16, v199
	v_and_b32_e32 v199, 0xffff0000, v199
	v_pk_add_f32 v[216:217], v[92:93], v[216:217]
	v_cvt_pk_bf16_f32 v210, v212, v213
	v_cvt_pk_bf16_f32 v211, v208, v209
	v_mul_f32_e32 v170, v170, v170
	v_cvt_pk_bf16_f32 v212, v216, v217
	v_cvt_pk_bf16_f32 v213, v214, v215
	v_mul_f32_e32 v196, v196, v196
	v_mul_f32_e32 v198, v198, v198
	v_mul_f32_e32 v199, v199, v199
	v_and_b32_e32 v209, 0xffff0000, v210
	v_and_b32_e32 v215, 0xffff0000, v211
	v_lshlrev_b32_e32 v208, 16, v210
	v_lshlrev_b32_e32 v214, 16, v211
	v_fmac_f32_e32 v170, v0, v0
	v_fmac_f32_e32 v196, v171, v171
	v_fmac_f32_e32 v198, v197, v197
	v_fmac_f32_e32 v199, v218, v218
	v_mul_f32_e32 v0, v209, v209
	v_mul_f32_e32 v171, v215, v215
	v_and_b32_e32 v217, 0xffff0000, v212
	v_and_b32_e32 v220, 0xffff0000, v213
	v_add_f32_e32 v170, v170, v196
	v_add_f32_e32 v196, v198, v199
	v_fmac_f32_e32 v0, v208, v208
	v_fmac_f32_e32 v171, v214, v214
	v_lshlrev_b32_e32 v216, 16, v212
	v_lshlrev_b32_e32 v219, 16, v213
	v_add_f32_e32 v170, v170, v196
	v_add_f32_e32 v0, v0, v171
	v_mul_f32_e32 v171, v217, v217
	v_mul_f32_e32 v196, v220, v220
	v_fmac_f32_e32 v171, v216, v216
	v_fmac_f32_e32 v196, v219, v219
	v_add_f32_e32 v171, v171, v196
	v_add_f32_e32 v0, v0, v171
	v_and_b32_e32 v171, 64, v163
	v_add_f32_e32 v170, v170, v0
	v_xor_b32_e32 v0, 16, v163
	v_add_u32_e32 v171, 64, v171
	v_cmp_lt_i32_e32 vcc, v0, v171
	global_store_dwordx4 v[172:173], v[210:213], off offset:256
	s_nop 0
	v_cndmask_b32_e32 v0, v163, v0, vcc
	v_lshlrev_b32_e32 v0, 2, v0
	v_mov_b32_e32 v196, v170
	s_nop 1
	v_permlane16_swap_b32_e32 v170, v196
	s_waitcnt lgkmcnt(0)
	v_add_f32_e32 v196, v170, v196
	v_xor_b32_e32 v170, 32, v163
	v_cmp_lt_i32_e32 vcc, v170, v171
	s_nop 1
	v_cndmask_b32_e32 v170, v163, v170, vcc
	v_lshlrev_b32_e32 v208, 2, v170
	v_mov_b32_e32 v197, v196
	s_nop 1
	v_permlane32_swap_b32_e32 v196, v197
	s_lshl_b32 vcc_lo, s57, 2
	s_ashr_i32 vcc_hi, vcc_lo, 31
	s_and_saveexec_b64 s[72:73], s[40:41]
	s_cbranch_execz .LBB7_1109
	v_lshlrev_b64 v[170:171], 6, v[184:185]
	v_lshl_add_u64 v[170:171], s[66:67], 0, v[170:171]
	v_lshl_add_u64 v[170:171], vcc, 2, v[170:171]
	s_lshl_b32 s20, s92, 2
	v_lshl_add_u64 v[170:171], v[170:171], 0, s[20:21]
	s_waitcnt lgkmcnt(0)
	v_add_f32_e32 v172, v196, v197
	global_store_dword v[170:171], v172, off
.LBB7_1109:
	s_or_b64 exec, exec, s[72:73]
	v_lshlrev_b32_e32 v170, 16, v152
	v_and_b32_e32 v171, 0xffff0000, v152
	v_lshlrev_b32_e32 v152, 16, v153
	v_and_b32_e32 v153, 0xffff0000, v153
	v_lshlrev_b32_e32 v172, 16, v154
	v_and_b32_e32 v173, 0xffff0000, v154
	v_lshlrev_b32_e32 v154, 16, v155
	v_and_b32_e32 v155, 0xffff0000, v155
	s_waitcnt lgkmcnt(0)
	v_pk_add_f32 v[196:197], v[122:123], v[152:153]
	v_pk_add_f32 v[152:153], v[120:121], v[170:171]
	v_pk_add_f32 v[170:171], v[118:119], v[154:155]
	v_pk_add_f32 v[154:155], v[116:117], v[172:173]
	v_cvt_pk_bf16_f32 v152, v152, v153
	v_cvt_pk_bf16_f32 v153, v196, v197
	s_nop 0
	v_cvt_pk_bf16_f32 v154, v154, v155
	v_cvt_pk_bf16_f32 v155, v170, v171
	v_lshl_add_u64 v[170:171], s[68:69], 0, v[194:195]
	v_lshl_add_u64 v[170:171], v[2:3], 1, v[170:171]
	global_store_dwordx4 v[170:171], v[152:155], off
	v_lshlrev_b32_e32 v172, 16, v152
	v_lshlrev_b32_e32 v173, 16, v153
	v_and_b32_e32 v152, 0xffff0000, v152
	v_and_b32_e32 v153, 0xffff0000, v153
	v_mul_f32_e32 v152, v152, v152
	v_mul_f32_e32 v153, v153, v153
	v_lshlrev_b32_e32 v185, 16, v154
	v_and_b32_e32 v154, 0xffff0000, v154
	v_lshlrev_b32_e32 v194, 16, v155
	v_and_b32_e32 v155, 0xffff0000, v155
	v_fmac_f32_e32 v152, v172, v172
	v_fmac_f32_e32 v153, v173, v173
	v_add_f32_e32 v152, v152, v153
	v_mul_f32_e32 v153, v154, v154
	v_mul_f32_e32 v154, v155, v155
	v_fmac_f32_e32 v153, v185, v185
	v_fmac_f32_e32 v154, v194, v194
	v_add_f32_e32 v153, v153, v154
	v_add_f32_e32 v185, v152, v153
	v_lshlrev_b32_e32 v152, 16, v148
	v_and_b32_e32 v153, 0xffff0000, v148
	v_lshlrev_b32_e32 v148, 16, v149
	v_and_b32_e32 v149, 0xffff0000, v149
	v_lshlrev_b32_e32 v154, 16, v150
	v_and_b32_e32 v155, 0xffff0000, v150
	v_lshlrev_b32_e32 v150, 16, v151
	v_and_b32_e32 v151, 0xffff0000, v151
	v_pk_add_f32 v[148:149], v[90:91], v[148:149]
	v_pk_add_f32 v[152:153], v[88:89], v[152:153]
	v_pk_add_f32 v[172:173], v[86:87], v[150:151]
	v_pk_add_f32 v[154:155], v[84:85], v[154:155]
	v_cvt_pk_bf16_f32 v150, v152, v153
	v_cvt_pk_bf16_f32 v151, v148, v149
	s_nop 0
	v_and_b32_e32 v149, 0xffff0000, v150
	v_cvt_pk_bf16_f32 v152, v154, v155
	v_lshlrev_b32_e32 v148, 16, v150
	v_and_b32_e32 v155, 0xffff0000, v151
	v_mul_f32_e32 v149, v149, v149
	v_lshlrev_b32_e32 v154, 16, v151
	v_fmac_f32_e32 v149, v148, v148
	v_mul_f32_e32 v148, v155, v155
	v_cvt_pk_bf16_f32 v153, v172, v173
	v_and_b32_e32 v173, 0xffff0000, v152
	v_and_b32_e32 v195, 0xffff0000, v153
	v_fmac_f32_e32 v148, v154, v154
	v_lshlrev_b32_e32 v172, 16, v152
	v_lshlrev_b32_e32 v194, 16, v153
	v_add_f32_e32 v148, v149, v148
	v_mul_f32_e32 v149, v173, v173
	v_mul_f32_e32 v154, v195, v195
	v_fmac_f32_e32 v149, v172, v172
	v_fmac_f32_e32 v154, v194, v194
	v_add_f32_e32 v149, v149, v154
	v_add_f32_e32 v148, v148, v149
	v_add_f32_e32 v148, v185, v148
	v_mov_b32_e32 v149, v148
	s_nop 1
	v_permlane16_swap_b32_e32 v148, v149
	global_store_dwordx4 v[170:171], v[150:153], off offset:256
	s_waitcnt lgkmcnt(0)
	v_add_f32_e32 v148, v148, v149
	v_mov_b32_e32 v149, v148
	s_nop 1
	v_permlane32_swap_b32_e32 v148, v149
	s_and_saveexec_b64 s[72:73], s[40:41]
	s_cbranch_execz .LBB7_1111
	v_lshlrev_b64 v[150:151], 6, v[192:193]
	v_lshl_add_u64 v[150:151], s[66:67], 0, v[150:151]
	v_lshl_add_u64 v[150:151], vcc, 2, v[150:151]
	s_lshl_b32 s20, s92, 2
	v_lshl_add_u64 v[150:151], v[150:151], 0, s[20:21]
	s_waitcnt lgkmcnt(0)
	v_add_f32_e32 v148, v148, v149
	global_store_dword v[150:151], v148, off
.LBB7_1111:
	s_or_b64 exec, exec, s[72:73]
	v_lshlrev_b32_e32 v148, 16, v144
	s_waitcnt lgkmcnt(0)
	v_and_b32_e32 v149, 0xffff0000, v144
	v_lshlrev_b32_e32 v144, 16, v145
	v_and_b32_e32 v145, 0xffff0000, v145
	v_lshlrev_b32_e32 v150, 16, v146
	v_and_b32_e32 v151, 0xffff0000, v146
	v_lshlrev_b32_e32 v146, 16, v147
	v_and_b32_e32 v147, 0xffff0000, v147
	v_pk_add_f32 v[152:153], v[114:115], v[144:145]
	v_pk_add_f32 v[144:145], v[112:113], v[148:149]
	v_pk_add_f32 v[148:149], v[110:111], v[146:147]
	v_pk_add_f32 v[146:147], v[108:109], v[150:151]
	v_cvt_pk_bf16_f32 v144, v144, v145
	v_cvt_pk_bf16_f32 v145, v152, v153
	s_nop 0
	v_cvt_pk_bf16_f32 v146, v146, v147
	v_cvt_pk_bf16_f32 v147, v148, v149
	v_lshl_add_u64 v[148:149], s[68:69], 0, v[188:189]
	v_lshl_add_u64 v[148:149], v[2:3], 1, v[148:149]
	global_store_dwordx4 v[148:149], v[144:147], off
	v_lshlrev_b32_e32 v150, 16, v144
	v_lshlrev_b32_e32 v151, 16, v145
	v_and_b32_e32 v144, 0xffff0000, v144
	v_and_b32_e32 v145, 0xffff0000, v145
	v_mul_f32_e32 v144, v144, v144
	v_mul_f32_e32 v145, v145, v145
	v_lshlrev_b32_e32 v152, 16, v146
	v_and_b32_e32 v146, 0xffff0000, v146
	v_lshlrev_b32_e32 v153, 16, v147
	v_and_b32_e32 v147, 0xffff0000, v147
	v_fmac_f32_e32 v144, v150, v150
	v_fmac_f32_e32 v145, v151, v151
	v_add_f32_e32 v144, v144, v145
	v_mul_f32_e32 v145, v146, v146
	v_mul_f32_e32 v146, v147, v147
	v_fmac_f32_e32 v145, v152, v152
	v_fmac_f32_e32 v146, v153, v153
	v_add_f32_e32 v145, v145, v146
	v_add_f32_e32 v152, v144, v145
	v_lshlrev_b32_e32 v144, 16, v140
	v_and_b32_e32 v145, 0xffff0000, v140
	v_lshlrev_b32_e32 v140, 16, v141
	v_and_b32_e32 v141, 0xffff0000, v141
	v_lshlrev_b32_e32 v146, 16, v142
	v_and_b32_e32 v147, 0xffff0000, v142
	v_lshlrev_b32_e32 v142, 16, v143
	v_and_b32_e32 v143, 0xffff0000, v143
	v_pk_add_f32 v[140:141], v[82:83], v[140:141]
	v_pk_add_f32 v[144:145], v[80:81], v[144:145]
	v_pk_add_f32 v[150:151], v[78:79], v[142:143]
	v_pk_add_f32 v[146:147], v[76:77], v[146:147]
	v_cvt_pk_bf16_f32 v142, v144, v145
	v_cvt_pk_bf16_f32 v143, v140, v141
	s_nop 0
	v_and_b32_e32 v141, 0xffff0000, v142
	v_cvt_pk_bf16_f32 v144, v146, v147
	v_lshlrev_b32_e32 v140, 16, v142
	v_and_b32_e32 v147, 0xffff0000, v143
	v_mul_f32_e32 v141, v141, v141
	v_lshlrev_b32_e32 v146, 16, v143
	v_fmac_f32_e32 v141, v140, v140
	v_mul_f32_e32 v140, v147, v147
	v_cvt_pk_bf16_f32 v145, v150, v151
	v_and_b32_e32 v151, 0xffff0000, v144
	v_and_b32_e32 v154, 0xffff0000, v145
	v_fmac_f32_e32 v140, v146, v146
	v_lshlrev_b32_e32 v150, 16, v144
	v_lshlrev_b32_e32 v153, 16, v145
	v_add_f32_e32 v140, v141, v140
	v_mul_f32_e32 v141, v151, v151
	v_mul_f32_e32 v146, v154, v154
	v_fmac_f32_e32 v141, v150, v150
	v_fmac_f32_e32 v146, v153, v153
	v_add_f32_e32 v141, v141, v146
	v_add_f32_e32 v140, v140, v141
	v_add_f32_e32 v140, v152, v140
	v_mov_b32_e32 v141, v140
	s_nop 1
	v_permlane16_swap_b32_e32 v140, v141
	global_store_dwordx4 v[148:149], v[142:145], off offset:256
	s_waitcnt lgkmcnt(0)
	v_add_f32_e32 v140, v140, v141
	v_mov_b32_e32 v141, v140
	s_nop 1
	v_permlane32_swap_b32_e32 v140, v141
	s_and_saveexec_b64 s[72:73], s[40:41]
	s_cbranch_execz .LBB7_1113
	v_lshlrev_b64 v[142:143], 6, v[186:187]
	v_lshl_add_u64 v[142:143], s[66:67], 0, v[142:143]
	v_lshl_add_u64 v[142:143], vcc, 2, v[142:143]
	s_lshl_b32 s20, s92, 2
	v_lshl_add_u64 v[142:143], v[142:143], 0, s[20:21]
	s_waitcnt lgkmcnt(0)
	v_add_f32_e32 v140, v140, v141
	global_store_dword v[142:143], v140, off
.LBB7_1113:
	s_or_b64 exec, exec, s[72:73]
	v_lshlrev_b32_e32 v140, 16, v136
	s_waitcnt lgkmcnt(0)
	v_and_b32_e32 v141, 0xffff0000, v136
	v_lshlrev_b32_e32 v136, 16, v137
	v_and_b32_e32 v137, 0xffff0000, v137
	v_lshlrev_b32_e32 v142, 16, v138
	v_and_b32_e32 v143, 0xffff0000, v138
	v_lshlrev_b32_e32 v138, 16, v139
	v_and_b32_e32 v139, 0xffff0000, v139
	v_pk_add_f32 v[144:145], v[106:107], v[136:137]
	v_pk_add_f32 v[136:137], v[104:105], v[140:141]
	v_pk_add_f32 v[140:141], v[102:103], v[138:139]
	v_pk_add_f32 v[138:139], v[100:101], v[142:143]
	v_cvt_pk_bf16_f32 v136, v136, v137
	v_cvt_pk_bf16_f32 v137, v144, v145
	s_nop 0
	v_cvt_pk_bf16_f32 v138, v138, v139
	v_cvt_pk_bf16_f32 v139, v140, v141
	v_lshl_add_u64 v[140:141], s[68:69], 0, v[158:159]
	v_lshl_add_u64 v[140:141], v[2:3], 1, v[140:141]
	global_store_dwordx4 v[140:141], v[136:139], off
	v_lshlrev_b32_e32 v142, 16, v136
	v_lshlrev_b32_e32 v143, 16, v137
	v_and_b32_e32 v136, 0xffff0000, v136
	v_and_b32_e32 v137, 0xffff0000, v137
	v_mul_f32_e32 v136, v136, v136
	v_mul_f32_e32 v137, v137, v137
	v_lshlrev_b32_e32 v144, 16, v138
	v_and_b32_e32 v138, 0xffff0000, v138
	v_lshlrev_b32_e32 v145, 16, v139
	v_and_b32_e32 v139, 0xffff0000, v139
	v_fmac_f32_e32 v136, v142, v142
	v_fmac_f32_e32 v137, v143, v143
	v_add_f32_e32 v136, v136, v137
	v_mul_f32_e32 v137, v138, v138
	v_mul_f32_e32 v138, v139, v139
	v_fmac_f32_e32 v137, v144, v144
	v_fmac_f32_e32 v138, v145, v145
	v_add_f32_e32 v137, v137, v138
	v_add_f32_e32 v144, v136, v137
	v_lshlrev_b32_e32 v136, 16, v132
	v_and_b32_e32 v137, 0xffff0000, v132
	v_lshlrev_b32_e32 v132, 16, v133
	v_and_b32_e32 v133, 0xffff0000, v133
	v_lshlrev_b32_e32 v138, 16, v134
	v_and_b32_e32 v139, 0xffff0000, v134
	v_lshlrev_b32_e32 v134, 16, v135
	v_and_b32_e32 v135, 0xffff0000, v135
	v_pk_add_f32 v[132:133], v[74:75], v[132:133]
	v_pk_add_f32 v[136:137], v[72:73], v[136:137]
	v_pk_add_f32 v[142:143], v[70:71], v[134:135]
	v_pk_add_f32 v[138:139], v[68:69], v[138:139]
	v_cvt_pk_bf16_f32 v134, v136, v137
	v_cvt_pk_bf16_f32 v135, v132, v133
	s_nop 0
	v_and_b32_e32 v133, 0xffff0000, v134
	v_cvt_pk_bf16_f32 v136, v138, v139
	v_lshlrev_b32_e32 v132, 16, v134
	v_and_b32_e32 v139, 0xffff0000, v135
	v_mul_f32_e32 v133, v133, v133
	v_lshlrev_b32_e32 v138, 16, v135
	v_fmac_f32_e32 v133, v132, v132
	v_mul_f32_e32 v132, v139, v139
	v_cvt_pk_bf16_f32 v137, v142, v143
	v_and_b32_e32 v143, 0xffff0000, v136
	v_and_b32_e32 v146, 0xffff0000, v137
	v_fmac_f32_e32 v132, v138, v138
	v_lshlrev_b32_e32 v142, 16, v136
	v_lshlrev_b32_e32 v145, 16, v137
	v_add_f32_e32 v132, v133, v132
	v_mul_f32_e32 v133, v143, v143
	v_mul_f32_e32 v138, v146, v146
	v_fmac_f32_e32 v133, v142, v142
	v_fmac_f32_e32 v138, v145, v145
	v_add_f32_e32 v133, v133, v138
	v_add_f32_e32 v132, v132, v133
	v_add_f32_e32 v132, v144, v132
	v_mov_b32_e32 v133, v132
	s_nop 1
	v_permlane16_swap_b32_e32 v132, v133
	global_store_dwordx4 v[140:141], v[134:137], off offset:256
	s_waitcnt lgkmcnt(0)
	v_add_f32_e32 v132, v132, v133
	v_mov_b32_e32 v133, v132
	s_nop 1
	v_permlane32_swap_b32_e32 v132, v133
	s_and_saveexec_b64 s[72:73], s[40:41]
	s_cbranch_execz .LBB7_1115
	v_lshlrev_b64 v[134:135], 6, v[156:157]
	v_lshl_add_u64 v[134:135], s[66:67], 0, v[134:135]
	v_lshl_add_u64 v[134:135], vcc, 2, v[134:135]
	s_lshl_b32 s20, s92, 2
	v_lshl_add_u64 v[134:135], v[134:135], 0, s[20:21]
	s_waitcnt lgkmcnt(0)
	v_add_f32_e32 v132, v132, v133
	global_store_dword v[134:135], v132, off
.LBB7_1115:
	s_or_b64 exec, exec, s[72:73]
	v_add_u32_e32 v198, 0x80, v184
	v_ashrrev_i32_e32 v199, 31, v198
	v_lshlrev_b64 v[170:171], 11, v[198:199]
	s_waitcnt lgkmcnt(0)
	v_lshl_add_u64 v[132:133], v[190:191], 0, v[170:171]
	v_mov_b64_e32 v[210:211], v[232:233]
	v_mov_b64_e32 v[212:213], v[234:235]
	v_mov_b64_e32 v[156:157], v[236:237]
	v_mov_b64_e32 v[158:159], v[238:239]
	v_add_u32_e32 v194, 0x90, v184
	v_ashrrev_i32_e32 v195, 31, v194
	v_add_u32_e32 v188, 0xa0, v184
	v_lshlrev_b64 v[196:197], 11, v[194:195]
	v_ashrrev_i32_e32 v189, 31, v188
	v_add_u32_e32 v184, 0xb0, v184
	v_lshl_add_u64 v[132:133], v[190:191], 0, v[196:197]
	v_lshlrev_b64 v[192:193], 11, v[188:189]
	v_ashrrev_i32_e32 v185, 31, v184
	v_mov_b64_e32 v[152:153], v[240:241]
	v_mov_b64_e32 v[154:155], v[242:243]
	v_mov_b64_e32 v[148:149], v[244:245]
	v_mov_b64_e32 v[150:151], v[246:247]
	v_lshl_add_u64 v[132:133], v[190:191], 0, v[192:193]
	v_lshlrev_b64 v[186:187], 11, v[184:185]
	global_load_dwordx4 v[144:147], v[132:133], off
	global_load_dwordx4 v[140:143], v[132:133], off offset:256
	v_lshl_add_u64 v[132:133], v[190:191], 0, v[186:187]
	global_load_dwordx4 v[136:139], v[132:133], off
	s_nop 0
	global_load_dwordx4 v[132:135], v[132:133], off offset:256
	v_lshl_add_u64 v[170:171], s[68:69], 0, v[170:171]
	v_lshl_add_u64 v[170:171], v[2:3], 1, v[170:171]
	s_waitcnt vmcnt(7)
	v_lshlrev_b32_e32 v172, 16, v210
	v_and_b32_e32 v173, 0xffff0000, v210
	v_lshlrev_b32_e32 v190, 16, v211
	v_and_b32_e32 v191, 0xffff0000, v211
	v_lshlrev_b32_e32 v210, 16, v212
	v_and_b32_e32 v211, 0xffff0000, v212
	v_lshlrev_b32_e32 v212, 16, v213
	v_and_b32_e32 v213, 0xffff0000, v213
	v_pk_add_f32 v[172:173], v[64:65], v[172:173]
	v_pk_add_f32 v[190:191], v[66:67], v[190:191]
	v_pk_add_f32 v[214:215], v[62:63], v[212:213]
	v_pk_add_f32 v[212:213], v[60:61], v[210:211]
	v_cvt_pk_bf16_f32 v210, v172, v173
	v_cvt_pk_bf16_f32 v211, v190, v191
	s_nop 0
	v_and_b32_e32 v173, 0xffff0000, v210
	v_lshlrev_b32_e32 v172, 16, v210
	v_and_b32_e32 v191, 0xffff0000, v211
	v_mul_f32_e32 v173, v173, v173
	v_cvt_pk_bf16_f32 v212, v212, v213
	v_lshlrev_b32_e32 v190, 16, v211
	v_fmac_f32_e32 v173, v172, v172
	v_mul_f32_e32 v172, v191, v191
	v_cvt_pk_bf16_f32 v213, v214, v215
	global_store_dwordx4 v[170:171], v[210:213], off
	v_lshlrev_b32_e32 v209, 16, v212
	v_fmac_f32_e32 v172, v190, v190
	v_and_b32_e32 v210, 0xffff0000, v212
	v_and_b32_e32 v212, 0xffff0000, v213
	v_lshlrev_b32_e32 v211, 16, v213
	v_add_f32_e32 v172, v173, v172
	v_mul_f32_e32 v173, v210, v210
	v_mul_f32_e32 v190, v212, v212
	v_fmac_f32_e32 v173, v209, v209
	v_fmac_f32_e32 v190, v211, v211
	v_add_f32_e32 v173, v173, v190
	v_add_f32_e32 v209, v172, v173
	s_waitcnt vmcnt(7)
	v_lshlrev_b32_e32 v172, 16, v156
	v_and_b32_e32 v173, 0xffff0000, v156
	v_lshlrev_b32_e32 v156, 16, v157
	v_and_b32_e32 v157, 0xffff0000, v157
	v_lshlrev_b32_e32 v190, 16, v158
	v_and_b32_e32 v191, 0xffff0000, v158
	v_lshlrev_b32_e32 v158, 16, v159
	v_and_b32_e32 v159, 0xffff0000, v159
	v_pk_add_f32 v[210:211], v[34:35], v[156:157]
	v_pk_add_f32 v[156:157], v[32:33], v[172:173]
	v_pk_add_f32 v[172:173], v[30:31], v[158:159]
	v_pk_add_f32 v[158:159], v[28:29], v[190:191]
	v_cvt_pk_bf16_f32 v156, v156, v157
	v_cvt_pk_bf16_f32 v157, v210, v211
	s_nop 0
	v_cvt_pk_bf16_f32 v158, v158, v159
	v_cvt_pk_bf16_f32 v159, v172, v173
	global_store_dwordx4 v[170:171], v[156:159], off offset:256
	v_lshlrev_b32_e32 v170, 16, v156
	v_lshlrev_b32_e32 v171, 16, v157
	v_and_b32_e32 v156, 0xffff0000, v156
	v_and_b32_e32 v157, 0xffff0000, v157
	v_mul_f32_e32 v156, v156, v156
	v_mul_f32_e32 v157, v157, v157
	v_lshlrev_b32_e32 v172, 16, v158
	v_and_b32_e32 v158, 0xffff0000, v158
	v_lshlrev_b32_e32 v173, 16, v159
	v_and_b32_e32 v159, 0xffff0000, v159
	v_fmac_f32_e32 v156, v170, v170
	v_fmac_f32_e32 v157, v171, v171
	v_add_f32_e32 v156, v156, v157
	v_mul_f32_e32 v157, v158, v158
	v_mul_f32_e32 v158, v159, v159
	v_fmac_f32_e32 v157, v172, v172
	v_fmac_f32_e32 v158, v173, v173
	v_add_f32_e32 v157, v157, v158
	v_add_f32_e32 v156, v156, v157
	v_add_f32_e32 v156, v209, v156
	v_mov_b32_e32 v157, v156
	s_nop 1
	v_permlane16_swap_b32_e32 v156, v157
	s_waitcnt lgkmcnt(0)
	v_add_f32_e32 v156, v156, v157
	v_mov_b32_e32 v157, v156
	s_nop 1
	v_permlane32_swap_b32_e32 v156, v157
	s_and_saveexec_b64 s[72:73], s[40:41]
	s_cbranch_execz .LBB7_1117
	v_lshlrev_b64 v[158:159], 6, v[198:199]
	v_lshl_add_u64 v[158:159], s[66:67], 0, v[158:159]
	v_lshl_add_u64 v[158:159], vcc, 2, v[158:159]
	s_lshl_b32 s20, s92, 2
	v_lshl_add_u64 v[158:159], v[158:159], 0, s[20:21]
	s_waitcnt lgkmcnt(0)
	v_add_f32_e32 v156, v156, v157
	global_store_dword v[158:159], v156, off
.LBB7_1117:
	s_or_b64 exec, exec, s[72:73]
	s_waitcnt vmcnt(7)
	v_lshlrev_b32_e32 v156, 16, v152
	s_waitcnt lgkmcnt(0)
	v_and_b32_e32 v157, 0xffff0000, v152
	v_lshlrev_b32_e32 v152, 16, v153
	v_and_b32_e32 v153, 0xffff0000, v153
	v_lshlrev_b32_e32 v158, 16, v154
	v_and_b32_e32 v159, 0xffff0000, v154
	v_lshlrev_b32_e32 v154, 16, v155
	v_and_b32_e32 v155, 0xffff0000, v155
	v_pk_add_f32 v[170:171], v[58:59], v[152:153]
	v_pk_add_f32 v[152:153], v[56:57], v[156:157]
	v_pk_add_f32 v[156:157], v[54:55], v[154:155]
	v_pk_add_f32 v[154:155], v[52:53], v[158:159]
	v_cvt_pk_bf16_f32 v152, v152, v153
	v_cvt_pk_bf16_f32 v153, v170, v171
	s_nop 0
	v_cvt_pk_bf16_f32 v154, v154, v155
	v_cvt_pk_bf16_f32 v155, v156, v157
	v_lshl_add_u64 v[156:157], s[68:69], 0, v[196:197]
	v_lshl_add_u64 v[156:157], v[2:3], 1, v[156:157]
	global_store_dwordx4 v[156:157], v[152:155], off
	v_lshlrev_b32_e32 v158, 16, v152
	v_lshlrev_b32_e32 v159, 16, v153
	v_and_b32_e32 v152, 0xffff0000, v152
	v_and_b32_e32 v153, 0xffff0000, v153
	v_mul_f32_e32 v152, v152, v152
	v_mul_f32_e32 v153, v153, v153
	v_lshlrev_b32_e32 v170, 16, v154
	v_and_b32_e32 v154, 0xffff0000, v154
	v_lshlrev_b32_e32 v171, 16, v155
	v_and_b32_e32 v155, 0xffff0000, v155
	v_fmac_f32_e32 v152, v158, v158
	v_fmac_f32_e32 v153, v159, v159
	v_add_f32_e32 v152, v152, v153
	v_mul_f32_e32 v153, v154, v154
	v_mul_f32_e32 v154, v155, v155
	v_fmac_f32_e32 v153, v170, v170
	v_fmac_f32_e32 v154, v171, v171
	v_add_f32_e32 v153, v153, v154
	v_add_f32_e32 v170, v152, v153
	s_waitcnt vmcnt(7)
	v_lshlrev_b32_e32 v152, 16, v148
	v_and_b32_e32 v153, 0xffff0000, v148
	v_lshlrev_b32_e32 v148, 16, v149
	v_and_b32_e32 v149, 0xffff0000, v149
	v_lshlrev_b32_e32 v154, 16, v150
	v_and_b32_e32 v155, 0xffff0000, v150
	v_lshlrev_b32_e32 v150, 16, v151
	v_and_b32_e32 v151, 0xffff0000, v151
	v_pk_add_f32 v[148:149], v[26:27], v[148:149]
	v_pk_add_f32 v[152:153], v[24:25], v[152:153]
	v_pk_add_f32 v[158:159], v[22:23], v[150:151]
	v_pk_add_f32 v[154:155], v[20:21], v[154:155]
	v_cvt_pk_bf16_f32 v150, v152, v153
	v_cvt_pk_bf16_f32 v151, v148, v149
	s_nop 0
	v_and_b32_e32 v149, 0xffff0000, v150
	v_cvt_pk_bf16_f32 v152, v154, v155
	v_lshlrev_b32_e32 v148, 16, v150
	v_and_b32_e32 v155, 0xffff0000, v151
	v_mul_f32_e32 v149, v149, v149
	v_lshlrev_b32_e32 v154, 16, v151
	v_fmac_f32_e32 v149, v148, v148
	v_mul_f32_e32 v148, v155, v155
	v_cvt_pk_bf16_f32 v153, v158, v159
	v_and_b32_e32 v159, 0xffff0000, v152
	v_and_b32_e32 v172, 0xffff0000, v153
	v_fmac_f32_e32 v148, v154, v154
	v_lshlrev_b32_e32 v158, 16, v152
	v_lshlrev_b32_e32 v171, 16, v153
	v_add_f32_e32 v148, v149, v148
	v_mul_f32_e32 v149, v159, v159
	v_mul_f32_e32 v154, v172, v172
	v_fmac_f32_e32 v149, v158, v158
	v_fmac_f32_e32 v154, v171, v171
	v_add_f32_e32 v149, v149, v154
	v_add_f32_e32 v148, v148, v149
	v_add_f32_e32 v148, v170, v148
	v_mov_b32_e32 v149, v148
	s_nop 1
	v_permlane16_swap_b32_e32 v148, v149
	global_store_dwordx4 v[156:157], v[150:153], off offset:256
	s_waitcnt lgkmcnt(0)
	v_add_f32_e32 v148, v148, v149
	v_mov_b32_e32 v149, v148
	s_nop 1
	v_permlane32_swap_b32_e32 v148, v149
	s_and_saveexec_b64 s[72:73], s[40:41]
	s_cbranch_execz .LBB7_1119
	v_lshlrev_b64 v[150:151], 6, v[194:195]
	v_lshl_add_u64 v[150:151], s[66:67], 0, v[150:151]
	v_lshl_add_u64 v[150:151], vcc, 2, v[150:151]
	s_lshl_b32 s20, s92, 2
	v_lshl_add_u64 v[150:151], v[150:151], 0, s[20:21]
	s_waitcnt lgkmcnt(0)
	v_add_f32_e32 v148, v148, v149
	global_store_dword v[150:151], v148, off
.LBB7_1119:
	s_or_b64 exec, exec, s[72:73]
	s_waitcnt vmcnt(7)
	v_lshlrev_b32_e32 v148, 16, v144
	s_waitcnt lgkmcnt(0)
	v_and_b32_e32 v149, 0xffff0000, v144
	v_lshlrev_b32_e32 v144, 16, v145
	v_and_b32_e32 v145, 0xffff0000, v145
	v_lshlrev_b32_e32 v150, 16, v146
	v_and_b32_e32 v151, 0xffff0000, v146
	v_lshlrev_b32_e32 v146, 16, v147
	v_and_b32_e32 v147, 0xffff0000, v147
	v_pk_add_f32 v[152:153], v[50:51], v[144:145]
	v_pk_add_f32 v[144:145], v[48:49], v[148:149]
	v_pk_add_f32 v[148:149], v[46:47], v[146:147]
	v_pk_add_f32 v[146:147], v[44:45], v[150:151]
	v_cvt_pk_bf16_f32 v144, v144, v145
	v_cvt_pk_bf16_f32 v145, v152, v153
	s_nop 0
	v_cvt_pk_bf16_f32 v146, v146, v147
	v_cvt_pk_bf16_f32 v147, v148, v149
	v_lshl_add_u64 v[148:149], s[68:69], 0, v[192:193]
	v_lshl_add_u64 v[148:149], v[2:3], 1, v[148:149]
	global_store_dwordx4 v[148:149], v[144:147], off
	v_lshlrev_b32_e32 v150, 16, v144
	v_lshlrev_b32_e32 v151, 16, v145
	v_and_b32_e32 v144, 0xffff0000, v144
	v_and_b32_e32 v145, 0xffff0000, v145
	v_mul_f32_e32 v144, v144, v144
	v_mul_f32_e32 v145, v145, v145
	v_lshlrev_b32_e32 v152, 16, v146
	v_and_b32_e32 v146, 0xffff0000, v146
	v_lshlrev_b32_e32 v153, 16, v147
	v_and_b32_e32 v147, 0xffff0000, v147
	v_fmac_f32_e32 v144, v150, v150
	v_fmac_f32_e32 v145, v151, v151
	v_add_f32_e32 v144, v144, v145
	v_mul_f32_e32 v145, v146, v146
	v_mul_f32_e32 v146, v147, v147
	v_fmac_f32_e32 v145, v152, v152
	v_fmac_f32_e32 v146, v153, v153
	v_add_f32_e32 v145, v145, v146
	v_add_f32_e32 v152, v144, v145
	s_waitcnt vmcnt(7)
	v_lshlrev_b32_e32 v144, 16, v140
	v_and_b32_e32 v145, 0xffff0000, v140
	v_lshlrev_b32_e32 v140, 16, v141
	v_and_b32_e32 v141, 0xffff0000, v141
	v_lshlrev_b32_e32 v146, 16, v142
	v_and_b32_e32 v147, 0xffff0000, v142
	v_lshlrev_b32_e32 v142, 16, v143
	v_and_b32_e32 v143, 0xffff0000, v143
	v_pk_add_f32 v[140:141], v[18:19], v[140:141]
	v_pk_add_f32 v[144:145], v[16:17], v[144:145]
	v_pk_add_f32 v[150:151], v[14:15], v[142:143]
	v_pk_add_f32 v[146:147], v[12:13], v[146:147]
	v_cvt_pk_bf16_f32 v142, v144, v145
	v_cvt_pk_bf16_f32 v143, v140, v141
	s_nop 0
	v_and_b32_e32 v141, 0xffff0000, v142
	v_cvt_pk_bf16_f32 v144, v146, v147
	v_lshlrev_b32_e32 v140, 16, v142
	v_and_b32_e32 v147, 0xffff0000, v143
	v_mul_f32_e32 v141, v141, v141
	v_lshlrev_b32_e32 v146, 16, v143
	v_fmac_f32_e32 v141, v140, v140
	v_mul_f32_e32 v140, v147, v147
	v_cvt_pk_bf16_f32 v145, v150, v151
	v_and_b32_e32 v151, 0xffff0000, v144
	v_and_b32_e32 v154, 0xffff0000, v145
	v_fmac_f32_e32 v140, v146, v146
	v_lshlrev_b32_e32 v150, 16, v144
	v_lshlrev_b32_e32 v153, 16, v145
	v_add_f32_e32 v140, v141, v140
	v_mul_f32_e32 v141, v151, v151
	v_mul_f32_e32 v146, v154, v154
	v_fmac_f32_e32 v141, v150, v150
	v_fmac_f32_e32 v146, v153, v153
	v_add_f32_e32 v141, v141, v146
	v_add_f32_e32 v140, v140, v141
	v_add_f32_e32 v140, v152, v140
	v_mov_b32_e32 v141, v140
	s_nop 1
	v_permlane16_swap_b32_e32 v140, v141
	global_store_dwordx4 v[148:149], v[142:145], off offset:256
	s_waitcnt lgkmcnt(0)
	v_add_f32_e32 v140, v140, v141
	v_mov_b32_e32 v141, v140
	s_nop 1
	v_permlane32_swap_b32_e32 v140, v141
	s_and_saveexec_b64 s[72:73], s[40:41]
	s_cbranch_execz .LBB7_1121
	v_lshlrev_b64 v[142:143], 6, v[188:189]
	v_lshl_add_u64 v[142:143], s[66:67], 0, v[142:143]
	v_lshl_add_u64 v[142:143], vcc, 2, v[142:143]
	s_lshl_b32 s20, s92, 2
	v_lshl_add_u64 v[142:143], v[142:143], 0, s[20:21]
	s_waitcnt lgkmcnt(0)
	v_add_f32_e32 v140, v140, v141
	global_store_dword v[142:143], v140, off
.LBB7_1121:
	s_or_b64 exec, exec, s[72:73]
	s_waitcnt vmcnt(7)
	v_lshlrev_b32_e32 v140, 16, v136
	s_waitcnt lgkmcnt(0)
	v_and_b32_e32 v141, 0xffff0000, v136
	v_lshlrev_b32_e32 v136, 16, v137
	v_and_b32_e32 v137, 0xffff0000, v137
	v_lshlrev_b32_e32 v142, 16, v138
	v_and_b32_e32 v143, 0xffff0000, v138
	v_lshlrev_b32_e32 v138, 16, v139
	v_and_b32_e32 v139, 0xffff0000, v139
	v_pk_add_f32 v[144:145], v[42:43], v[136:137]
	v_pk_add_f32 v[136:137], v[40:41], v[140:141]
	v_pk_add_f32 v[140:141], v[38:39], v[138:139]
	v_pk_add_f32 v[138:139], v[36:37], v[142:143]
	v_cvt_pk_bf16_f32 v136, v136, v137
	v_cvt_pk_bf16_f32 v137, v144, v145
	s_nop 0
	v_cvt_pk_bf16_f32 v138, v138, v139
	v_cvt_pk_bf16_f32 v139, v140, v141
	v_lshl_add_u64 v[140:141], s[68:69], 0, v[186:187]
	v_lshl_add_u64 v[140:141], v[2:3], 1, v[140:141]
	v_and_b32_e32 v3, 0xffff0000, v136
	global_store_dwordx4 v[140:141], v[136:139], off
	v_lshlrev_b32_e32 v2, 16, v136
	v_mul_f32_e32 v3, v3, v3
	v_lshlrev_b32_e32 v136, 16, v137
	v_and_b32_e32 v137, 0xffff0000, v137
	v_fmac_f32_e32 v3, v2, v2
	v_mul_f32_e32 v2, v137, v137
	v_lshlrev_b32_e32 v142, 16, v138
	v_and_b32_e32 v138, 0xffff0000, v138
	v_lshlrev_b32_e32 v143, 16, v139
	v_and_b32_e32 v139, 0xffff0000, v139
	v_fmac_f32_e32 v2, v136, v136
	v_add_f32_e32 v2, v3, v2
	v_mul_f32_e32 v3, v138, v138
	v_mul_f32_e32 v136, v139, v139
	v_fmac_f32_e32 v3, v142, v142
	v_fmac_f32_e32 v136, v143, v143
	v_add_f32_e32 v3, v3, v136
	v_add_f32_e32 v144, v2, v3
	s_waitcnt vmcnt(7)
	v_lshlrev_b32_e32 v2, 16, v132
	v_and_b32_e32 v3, 0xffff0000, v132
	v_lshlrev_b32_e32 v132, 16, v133
	v_and_b32_e32 v133, 0xffff0000, v133
	v_pk_add_f32 v[2:3], v[8:9], v[2:3]
	v_lshlrev_b32_e32 v136, 16, v134
	v_and_b32_e32 v137, 0xffff0000, v134
	v_lshlrev_b32_e32 v134, 16, v135
	v_and_b32_e32 v135, 0xffff0000, v135
	v_pk_add_f32 v[138:139], v[10:11], v[132:133]
	v_cvt_pk_bf16_f32 v132, v2, v3
	v_pk_add_f32 v[142:143], v[6:7], v[134:135]
	v_and_b32_e32 v3, 0xffff0000, v132
	v_pk_add_f32 v[134:135], v[4:5], v[136:137]
	v_cvt_pk_bf16_f32 v133, v138, v139
	v_lshlrev_b32_e32 v2, 16, v132
	v_and_b32_e32 v137, 0xffff0000, v133
	v_mul_f32_e32 v3, v3, v3
	v_lshlrev_b32_e32 v136, 16, v133
	v_fmac_f32_e32 v3, v2, v2
	v_mul_f32_e32 v2, v137, v137
	v_cvt_pk_bf16_f32 v134, v134, v135
	v_cvt_pk_bf16_f32 v135, v142, v143
	v_fmac_f32_e32 v2, v136, v136
	v_and_b32_e32 v139, 0xffff0000, v134
	v_and_b32_e32 v143, 0xffff0000, v135
	v_lshlrev_b32_e32 v138, 16, v134
	v_lshlrev_b32_e32 v142, 16, v135
	v_add_f32_e32 v2, v3, v2
	v_mul_f32_e32 v3, v139, v139
	v_mul_f32_e32 v136, v143, v143
	v_fmac_f32_e32 v3, v138, v138
	v_fmac_f32_e32 v136, v142, v142
	v_add_f32_e32 v3, v3, v136
	v_add_f32_e32 v2, v2, v3
	v_add_f32_e32 v2, v144, v2
	v_mov_b32_e32 v0, v2
	s_nop 1
	v_permlane16_swap_b32_e32 v2, v0
	global_store_dwordx4 v[140:141], v[132:135], off offset:256
	s_waitcnt lgkmcnt(0)
	v_add_f32_e32 v0, v2, v0
	v_mov_b32_e32 v2, v0
	s_nop 1
	v_permlane32_swap_b32_e32 v0, v2
	s_and_saveexec_b64 s[72:73], s[40:41]
	s_cbranch_execz .LBB7_1123
	v_lshlrev_b64 v[132:133], 6, v[184:185]
	v_lshl_add_u64 v[132:133], s[66:67], 0, v[132:133]
	v_lshl_add_u64 v[132:133], vcc, 2, v[132:133]
	s_lshl_b32 s20, s92, 2
	v_lshl_add_u64 v[132:133], v[132:133], 0, s[20:21]
	s_waitcnt lgkmcnt(0)
	v_add_f32_e32 v0, v0, v2
	global_store_dword v[132:133], v0, off

.LBB7_1199:
	v_lshl_add_u32 v190, s10, 8, v149
	v_ashrrev_i32_e32 v191, 31, v190
	v_lshlrev_b64 v[190:191], 6, v[190:191]
	v_lshl_add_u64 v[190:191], v[140:141], 0, v[190:191]
	global_load_dwordx4 v[204:207], v[190:191], off
	global_load_dwordx4 v[208:211], v[190:191], off offset:1024
	global_load_dwordx4 v[212:215], v[190:191], off offset:2048
	global_load_dwordx4 v[216:219], v[190:191], off offset:3072
	v_add_co_u32_e32 v190, vcc, 0x2000, v190
	s_nop 1
	v_addc_co_u32_e32 v191, vcc, 0, v191, vcc
	global_load_dwordx4 v[220:223], v[190:191], off
	global_load_dwordx4 v[224:227], v[190:191], off offset:1024
	global_load_dwordx4 v[228:231], v[190:191], off offset:2048
	global_load_dwordx4 v[232:235], v[190:191], off offset:3072
	v_and_b32_e32 v131, 64, v163
	v_xor_b32_e32 v130, 16, v163
	v_add_u32_e32 v131, 64, v131
	v_cmp_lt_i32_e32 vcc, v130, v131
	v_lshl_add_u32 v146, s10, 8, v149
	v_ashrrev_i32_e32 v147, 31, v146
	v_cndmask_b32_e32 v130, v163, v130, vcc
	v_lshlrev_b32_e32 v183, 2, v130
	v_xor_b32_e32 v130, 32, v163
	v_cmp_lt_i32_e32 vcc, v130, v131
	s_mov_b32 s10, 0x358637bd
	v_mov_b64_e32 v[178:179], s[10:11]
	v_cndmask_b32_e32 v130, v163, v130, vcc
	v_lshlrev_b32_e32 v175, 2, v130
	v_lshlrev_b64 v[130:131], 6, v[146:147]
	v_lshl_add_u64 v[130:131], v[140:141], 0, v[130:131]
	v_add_u32_e32 v180, 0x80, v146
	v_ashrrev_i32_e32 v181, 31, v180
	v_add_u32_e32 v176, 0x90, v146
	v_ashrrev_i32_e32 v177, 31, v176
	v_add_u32_e32 v186, 0xa0, v146
	v_ashrrev_i32_e32 v187, 31, v186
	v_add_u32_e32 v184, 0xb0, v146
	v_ashrrev_i32_e32 v185, 31, v184
	s_mov_b64 s[16:17], -1
	s_waitcnt vmcnt(0)
	v_mov_b64_e32 v[130:131], v[204:205]
	v_mov_b64_e32 v[132:133], v[206:207]
	v_mov_b32_e32 v150, v131
	v_mov_b32_e32 v151, v132
	v_mov_b32_e32 v131, v133
	v_pk_add_f32 v[156:157], v[150:151], v[130:131]
	v_or_b32_e32 v150, 16, v146
	v_ashrrev_i32_e32 v151, 31, v150
	v_lshlrev_b64 v[130:131], 6, v[150:151]
	v_lshl_add_u64 v[130:131], v[140:141], 0, v[130:131]
	v_mov_b64_e32 v[130:131], v[208:209]
	v_mov_b64_e32 v[132:133], v[210:211]
	v_mov_b32_e32 v158, v131
	v_mov_b32_e32 v159, v132
	v_mov_b32_e32 v131, v133
	v_pk_add_f32 v[130:131], v[158:159], v[130:131]
	v_mov_b32_e32 v133, v156
	v_mov_b32_e32 v132, v130
	v_mov_b32_e32 v156, v131
	v_pk_add_f32 v[130:131], v[132:133], v[156:157]
	v_mov_b32_e32 v133, v131
	s_nop 1
	v_permlane16_swap_b32_e32 v131, v133
	v_mov_b32_e32 v132, v130
	s_nop 1
	v_permlane16_swap_b32_e32 v130, v132
	v_or_b32_e32 v158, 32, v146
	v_ashrrev_i32_e32 v159, 31, v158
	s_waitcnt lgkmcnt(0)
	v_pk_add_f32 v[130:131], v[130:131], v[132:133]
	v_mov_b32_e32 v133, v131
	s_nop 1
	v_permlane32_swap_b32_e32 v131, v133
	v_mov_b32_e32 v132, v130
	s_nop 1
	v_permlane32_swap_b32_e32 v130, v132
	s_waitcnt lgkmcnt(0)
	v_pk_add_f32 v[130:131], v[130:131], v[132:133]
	s_nop 0
	v_pk_fma_f32 v[130:131], v[130:131], s[26:27], v[178:179] op_sel_hi:[1,0,0]
	s_nop 0
	v_mul_f32_e32 v132, 0x4b800000, v131
	v_cmp_gt_f32_e64 s[42:43], s11, v131
	v_cmp_gt_f32_e32 vcc, s11, v130
	s_nop 0
	v_cndmask_b32_e64 v131, v131, v132, s[42:43]
	v_rsq_f32_e32 v131, v131
	s_nop 0
	v_mul_f32_e32 v132, 0x45800000, v131
	v_cndmask_b32_e64 v152, v131, v132, s[42:43]
	v_mul_f32_e32 v131, 0x4b800000, v130
	v_cndmask_b32_e32 v130, v130, v131, vcc
	v_rsq_f32_e32 v130, v130
	v_pk_mul_f32 v[128:129], v[128:129], v[152:153] op_sel_hi:[1,0]
	v_pk_mul_f32 v[126:127], v[126:127], v[152:153] op_sel_hi:[1,0]
	v_pk_mul_f32 v[120:121], v[120:121], v[152:153] op_sel_hi:[1,0]
	v_mul_f32_e32 v131, 0x45800000, v130
	v_cndmask_b32_e32 v148, v130, v131, vcc
	v_lshlrev_b64 v[130:131], 6, v[158:159]
	v_lshl_add_u64 v[130:131], v[140:141], 0, v[130:131]
	v_pk_mul_f32 v[118:119], v[118:119], v[152:153] op_sel_hi:[1,0]
	v_pk_mul_f32 v[112:113], v[112:113], v[148:149] op_sel_hi:[1,0]
	v_pk_mul_f32 v[110:111], v[110:111], v[148:149] op_sel_hi:[1,0]
	v_pk_mul_f32 v[104:105], v[104:105], v[148:149] op_sel_hi:[1,0]
	v_pk_mul_f32 v[102:103], v[102:103], v[148:149] op_sel_hi:[1,0]
	v_mov_b64_e32 v[130:131], v[212:213]
	v_mov_b64_e32 v[132:133], v[214:215]
	v_mov_b32_e32 v156, v131
	v_mov_b32_e32 v157, v132
	v_mov_b32_e32 v131, v133
	v_pk_add_f32 v[170:171], v[156:157], v[130:131]
	v_or_b32_e32 v156, 48, v146
	v_ashrrev_i32_e32 v157, 31, v156
	v_lshlrev_b64 v[130:131], 6, v[156:157]
	v_lshl_add_u64 v[130:131], v[140:141], 0, v[130:131]
	v_lshlrev_b64 v[146:147], 11, v[146:147]
	v_mov_b64_e32 v[130:131], v[216:217]
	v_mov_b64_e32 v[132:133], v[218:219]
	v_mov_b32_e32 v172, v131
	v_mov_b32_e32 v173, v132
	v_mov_b32_e32 v131, v133
	v_pk_add_f32 v[130:131], v[172:173], v[130:131]
	v_mov_b32_e32 v133, v170
	v_mov_b32_e32 v132, v130
	v_mov_b32_e32 v170, v131
	v_pk_add_f32 v[130:131], v[132:133], v[170:171]
	v_mov_b32_e32 v133, v131
	s_nop 1
	v_permlane16_swap_b32_e32 v131, v133
	v_mov_b32_e32 v132, v130
	s_nop 1
	v_permlane16_swap_b32_e32 v130, v132
	s_waitcnt lgkmcnt(0)
	v_pk_add_f32 v[130:131], v[130:131], v[132:133]
	v_mov_b32_e32 v133, v131
	s_nop 1
	v_permlane32_swap_b32_e32 v131, v133
	v_mov_b32_e32 v132, v130
	s_nop 1
	v_permlane32_swap_b32_e32 v130, v132
	s_waitcnt lgkmcnt(0)
	v_pk_add_f32 v[130:131], v[130:131], v[132:133]
	s_nop 0
	v_pk_fma_f32 v[130:131], v[130:131], s[26:27], v[178:179] op_sel_hi:[1,0,0]
	s_nop 0
	v_mul_f32_e32 v132, 0x4b800000, v131
	v_cmp_gt_f32_e64 s[42:43], s11, v131
	v_cmp_gt_f32_e32 vcc, s11, v130
	s_nop 0
	v_cndmask_b32_e64 v131, v131, v132, s[42:43]
	v_rsq_f32_e32 v131, v131
	s_nop 0
	v_mul_f32_e32 v132, 0x45800000, v131
	v_cndmask_b32_e64 v174, v131, v132, s[42:43]
	v_mul_f32_e32 v131, 0x4b800000, v130
	v_cndmask_b32_e32 v130, v130, v131, vcc
	v_rsq_f32_e32 v130, v130
	v_pk_mul_f32 v[96:97], v[96:97], v[174:175] op_sel_hi:[1,0]
	v_pk_mul_f32 v[94:95], v[94:95], v[174:175] op_sel_hi:[1,0]
	v_pk_mul_f32 v[88:89], v[88:89], v[174:175] op_sel_hi:[1,0]
	v_mul_f32_e32 v131, 0x45800000, v130
	v_cndmask_b32_e32 v154, v130, v131, vcc
	v_lshlrev_b64 v[130:131], 6, v[180:181]
	v_lshl_add_u64 v[130:131], v[140:141], 0, v[130:131]
	v_pk_mul_f32 v[86:87], v[86:87], v[174:175] op_sel_hi:[1,0]
	v_pk_mul_f32 v[80:81], v[80:81], v[154:155] op_sel_hi:[1,0]
	v_pk_mul_f32 v[78:79], v[78:79], v[154:155] op_sel_hi:[1,0]
	v_pk_mul_f32 v[72:73], v[72:73], v[154:155] op_sel_hi:[1,0]
	v_pk_mul_f32 v[70:71], v[70:71], v[154:155] op_sel_hi:[1,0]
	v_mov_b64_e32 v[130:131], v[220:221]
	v_mov_b64_e32 v[132:133], v[222:223]
	v_mov_b32_e32 v170, v131
	v_mov_b32_e32 v171, v132
	v_mov_b32_e32 v131, v133
	v_pk_add_f32 v[170:171], v[170:171], v[130:131]
	v_lshlrev_b64 v[130:131], 6, v[176:177]
	v_lshl_add_u64 v[130:131], v[140:141], 0, v[130:131]
	v_mov_b64_e32 v[130:131], v[224:225]
	v_mov_b64_e32 v[132:133], v[226:227]
	v_mov_b32_e32 v172, v131
	v_mov_b32_e32 v173, v132
	v_mov_b32_e32 v131, v133
	v_pk_add_f32 v[130:131], v[172:173], v[130:131]
	v_mov_b32_e32 v133, v170
	v_mov_b32_e32 v132, v130
	v_mov_b32_e32 v170, v131
	v_pk_add_f32 v[130:131], v[132:133], v[170:171]
	v_mov_b32_e32 v133, v131
	s_nop 1
	v_permlane16_swap_b32_e32 v131, v133
	v_mov_b32_e32 v132, v130
	s_nop 1
	v_permlane16_swap_b32_e32 v130, v132
	v_lshl_add_u64 v[172:173], s[94:95], 0, v[146:147]
	s_waitcnt lgkmcnt(0)
	v_pk_add_f32 v[130:131], v[130:131], v[132:133]
	v_mov_b32_e32 v133, v131
	s_nop 1
	v_permlane32_swap_b32_e32 v131, v133
	v_mov_b32_e32 v132, v130
	s_nop 1
	v_permlane32_swap_b32_e32 v130, v132
	s_waitcnt lgkmcnt(0)
	v_pk_add_f32 v[130:131], v[130:131], v[132:133]
	s_nop 0
	v_pk_fma_f32 v[130:131], v[130:131], s[26:27], v[178:179] op_sel_hi:[1,0,0]
	s_nop 0
	v_mul_f32_e32 v132, 0x4b800000, v131
	v_cmp_gt_f32_e64 s[42:43], s11, v131
	v_cmp_gt_f32_e32 vcc, s11, v130
	s_nop 0
	v_cndmask_b32_e64 v131, v131, v132, s[42:43]
	v_rsq_f32_e32 v131, v131
	s_nop 0
	v_mul_f32_e32 v132, 0x45800000, v131
	v_cndmask_b32_e64 v182, v131, v132, s[42:43]
	v_mul_f32_e32 v131, 0x4b800000, v130
	v_cndmask_b32_e32 v130, v130, v131, vcc
	v_rsq_f32_e32 v130, v130
	v_pk_mul_f32 v[64:65], v[64:65], v[182:183] op_sel_hi:[1,0]
	v_pk_mul_f32 v[62:63], v[62:63], v[182:183] op_sel_hi:[1,0]
	v_pk_mul_f32 v[56:57], v[56:57], v[182:183] op_sel_hi:[1,0]
	v_mul_f32_e32 v131, 0x45800000, v130
	v_cndmask_b32_e32 v160, v130, v131, vcc
	v_lshlrev_b64 v[130:131], 6, v[186:187]
	v_lshl_add_u64 v[130:131], v[140:141], 0, v[130:131]
	v_pk_mul_f32 v[54:55], v[54:55], v[182:183] op_sel_hi:[1,0]
	v_pk_mul_f32 v[48:49], v[48:49], v[160:161] op_sel_hi:[1,0]
	v_pk_mul_f32 v[46:47], v[46:47], v[160:161] op_sel_hi:[1,0]
	v_pk_mul_f32 v[40:41], v[40:41], v[160:161] op_sel_hi:[1,0]
	v_pk_mul_f32 v[38:39], v[38:39], v[160:161] op_sel_hi:[1,0]
	v_mov_b64_e32 v[130:131], v[228:229]
	v_mov_b64_e32 v[132:133], v[230:231]
	v_mov_b32_e32 v170, v131
	v_mov_b32_e32 v171, v132
	v_mov_b32_e32 v131, v133
	v_pk_add_f32 v[188:189], v[170:171], v[130:131]
	v_lshlrev_b64 v[130:131], 6, v[184:185]
	v_lshl_add_u64 v[130:131], v[140:141], 0, v[130:131]
	v_mov_b64_e32 v[130:131], v[232:233]
	v_mov_b64_e32 v[132:133], v[234:235]
	v_mov_b32_e32 v170, v131
	v_mov_b32_e32 v171, v132
	v_mov_b32_e32 v131, v133
	v_pk_add_f32 v[130:131], v[170:171], v[130:131]
	v_lshl_or_b32 v170, s38, 8, v155
	v_mov_b32_e32 v132, v130
	v_mov_b32_e32 v133, v188
	v_mov_b32_e32 v188, v131
	v_ashrrev_i32_e32 v171, 31, v170
	v_pk_add_f32 v[130:131], v[132:133], v[188:189]
	v_lshlrev_b64 v[146:147], 1, v[170:171]
	v_mov_b32_e32 v133, v131
	s_nop 1
	v_permlane16_swap_b32_e32 v131, v133
	v_mov_b32_e32 v132, v130
	s_nop 1
	v_permlane16_swap_b32_e32 v130, v132
	v_lshl_add_u64 v[170:171], v[172:173], 0, v[146:147]
	v_pk_mul_f32 v[172:173], v[124:125], v[152:153] op_sel_hi:[1,0]
	v_pk_mul_f32 v[124:125], v[122:123], v[152:153] op_sel_hi:[1,0]
	v_cvt_pk_bf16_f32 v122, v126, v127
	v_cvt_pk_bf16_f32 v123, v128, v129
	s_waitcnt lgkmcnt(0)
	v_pk_add_f32 v[130:131], v[130:131], v[132:133]
	v_cvt_pk_bf16_f32 v124, v124, v125
	v_cvt_pk_bf16_f32 v125, v172, v173
	global_store_dwordx4 v[170:171], v[122:125], off
	v_mov_b32_e32 v133, v131
	s_nop 1
	v_permlane32_swap_b32_e32 v131, v133
	v_mov_b32_e32 v132, v130
	s_nop 1
	v_permlane32_swap_b32_e32 v130, v132
	v_pk_mul_f32 v[122:123], v[116:117], v[152:153] op_sel_hi:[1,0]
	v_pk_mul_f32 v[116:117], v[114:115], v[152:153] op_sel_hi:[1,0]
	v_cvt_pk_bf16_f32 v114, v118, v119
	v_cvt_pk_bf16_f32 v115, v120, v121
	s_waitcnt lgkmcnt(0)
	v_pk_add_f32 v[130:131], v[130:131], v[132:133]
	v_cvt_pk_bf16_f32 v116, v116, v117
	v_cvt_pk_bf16_f32 v117, v122, v123
	global_store_dwordx4 v[170:171], v[114:117], off offset:256
	v_pk_fma_f32 v[130:131], v[130:131], s[26:27], v[178:179] op_sel_hi:[1,0,0]
	s_nop 0
	v_lshlrev_b64 v[114:115], 11, v[150:151]
	v_lshl_add_u64 v[114:115], s[94:95], 0, v[114:115]
	v_lshl_add_u64 v[114:115], v[114:115], 0, v[146:147]
	v_pk_mul_f32 v[116:117], v[108:109], v[148:149] op_sel_hi:[1,0]
	v_pk_mul_f32 v[108:109], v[106:107], v[148:149] op_sel_hi:[1,0]
	v_cvt_pk_bf16_f32 v106, v110, v111
	v_cvt_pk_bf16_f32 v107, v112, v113
	v_mul_f32_e32 v132, 0x4b800000, v131
	v_cvt_pk_bf16_f32 v108, v108, v109
	v_cvt_pk_bf16_f32 v109, v116, v117
	global_store_dwordx4 v[114:115], v[106:109], off
	v_cmp_gt_f32_e64 s[42:43], s11, v131
	v_cmp_gt_f32_e32 vcc, s11, v130
	v_pk_mul_f32 v[106:107], v[100:101], v[148:149] op_sel_hi:[1,0]
	v_pk_mul_f32 v[100:101], v[98:99], v[148:149] op_sel_hi:[1,0]
	v_cvt_pk_bf16_f32 v98, v102, v103
	v_cvt_pk_bf16_f32 v99, v104, v105
	v_cndmask_b32_e64 v131, v131, v132, s[42:43]
	v_cvt_pk_bf16_f32 v100, v100, v101
	v_cvt_pk_bf16_f32 v101, v106, v107
	global_store_dwordx4 v[114:115], v[98:101], off offset:256
	v_rsq_f32_e32 v131, v131
	s_nop 0
	v_lshlrev_b64 v[98:99], 11, v[158:159]
	v_lshl_add_u64 v[98:99], s[94:95], 0, v[98:99]
	v_lshl_add_u64 v[98:99], v[98:99], 0, v[146:147]
	v_pk_mul_f32 v[100:101], v[92:93], v[174:175] op_sel_hi:[1,0]
	v_pk_mul_f32 v[92:93], v[90:91], v[174:175] op_sel_hi:[1,0]
	v_cvt_pk_bf16_f32 v90, v94, v95
	v_cvt_pk_bf16_f32 v91, v96, v97
	v_mul_f32_e32 v132, 0x45800000, v131
	v_cvt_pk_bf16_f32 v92, v92, v93
	v_cvt_pk_bf16_f32 v93, v100, v101
	global_store_dwordx4 v[98:99], v[90:93], off
	v_cndmask_b32_e64 v132, v131, v132, s[42:43]
	v_mul_f32_e32 v131, 0x4b800000, v130
	v_pk_mul_f32 v[90:91], v[84:85], v[174:175] op_sel_hi:[1,0]
	v_pk_mul_f32 v[84:85], v[82:83], v[174:175] op_sel_hi:[1,0]
	v_cvt_pk_bf16_f32 v82, v86, v87
	v_cvt_pk_bf16_f32 v83, v88, v89
	v_cndmask_b32_e32 v130, v130, v131, vcc
	v_cvt_pk_bf16_f32 v84, v84, v85
	v_cvt_pk_bf16_f32 v85, v90, v91
	global_store_dwordx4 v[98:99], v[82:85], off offset:256
	v_rsq_f32_e32 v130, v130
	v_pk_mul_f32 v[32:33], v[32:33], v[132:133] op_sel_hi:[1,0]
	v_lshlrev_b64 v[82:83], 11, v[156:157]
	v_lshl_add_u64 v[82:83], s[94:95], 0, v[82:83]
	v_lshl_add_u64 v[82:83], v[82:83], 0, v[146:147]
	v_pk_mul_f32 v[84:85], v[76:77], v[154:155] op_sel_hi:[1,0]
	v_pk_mul_f32 v[76:77], v[74:75], v[154:155] op_sel_hi:[1,0]
	v_cvt_pk_bf16_f32 v74, v78, v79
	v_cvt_pk_bf16_f32 v75, v80, v81
	v_pk_mul_f32 v[30:31], v[30:31], v[132:133] op_sel_hi:[1,0]
	v_cvt_pk_bf16_f32 v76, v76, v77
	v_cvt_pk_bf16_f32 v77, v84, v85
	global_store_dwordx4 v[82:83], v[74:77], off
	v_pk_mul_f32 v[24:25], v[24:25], v[132:133] op_sel_hi:[1,0]
	v_pk_mul_f32 v[22:23], v[22:23], v[132:133] op_sel_hi:[1,0]
	v_pk_mul_f32 v[74:75], v[68:69], v[154:155] op_sel_hi:[1,0]
	v_pk_mul_f32 v[68:69], v[66:67], v[154:155] op_sel_hi:[1,0]
	v_cvt_pk_bf16_f32 v66, v70, v71
	v_cvt_pk_bf16_f32 v67, v72, v73
	v_mul_f32_e32 v131, 0x45800000, v130
	v_cvt_pk_bf16_f32 v68, v68, v69
	v_cvt_pk_bf16_f32 v69, v74, v75
	global_store_dwordx4 v[82:83], v[66:69], off offset:256
	v_cndmask_b32_e32 v130, v130, v131, vcc
	v_pk_mul_f32 v[16:17], v[16:17], v[130:131] op_sel_hi:[1,0]
	v_lshlrev_b64 v[66:67], 11, v[180:181]
	v_lshl_add_u64 v[66:67], s[94:95], 0, v[66:67]
	v_lshl_add_u64 v[66:67], v[66:67], 0, v[146:147]
	v_pk_mul_f32 v[68:69], v[60:61], v[182:183] op_sel_hi:[1,0]
	v_pk_mul_f32 v[60:61], v[58:59], v[182:183] op_sel_hi:[1,0]
	v_cvt_pk_bf16_f32 v58, v62, v63
	v_cvt_pk_bf16_f32 v59, v64, v65
	v_pk_mul_f32 v[14:15], v[14:15], v[130:131] op_sel_hi:[1,0]
	v_cvt_pk_bf16_f32 v60, v60, v61
	v_cvt_pk_bf16_f32 v61, v68, v69
	global_store_dwordx4 v[66:67], v[58:61], off
	v_pk_mul_f32 v[8:9], v[8:9], v[130:131] op_sel_hi:[1,0]
	v_pk_mul_f32 v[6:7], v[6:7], v[130:131] op_sel_hi:[1,0]
	v_pk_mul_f32 v[58:59], v[52:53], v[182:183] op_sel_hi:[1,0]
	v_pk_mul_f32 v[52:53], v[50:51], v[182:183] op_sel_hi:[1,0]
	v_cvt_pk_bf16_f32 v50, v54, v55
	v_cvt_pk_bf16_f32 v51, v56, v57
	s_andn2_b64 vcc, exec, s[40:41]
	v_cvt_pk_bf16_f32 v52, v52, v53
	v_cvt_pk_bf16_f32 v53, v58, v59
	global_store_dwordx4 v[66:67], v[50:53], off offset:256
	s_nop 1
	v_lshlrev_b64 v[50:51], 11, v[176:177]
	v_lshl_add_u64 v[50:51], s[94:95], 0, v[50:51]
	v_lshl_add_u64 v[50:51], v[50:51], 0, v[146:147]
	v_pk_mul_f32 v[52:53], v[44:45], v[160:161] op_sel_hi:[1,0]
	v_pk_mul_f32 v[44:45], v[42:43], v[160:161] op_sel_hi:[1,0]
	v_cvt_pk_bf16_f32 v42, v46, v47
	v_cvt_pk_bf16_f32 v43, v48, v49
	s_nop 0
	v_cvt_pk_bf16_f32 v44, v44, v45
	v_cvt_pk_bf16_f32 v45, v52, v53
	global_store_dwordx4 v[50:51], v[42:45], off
	s_nop 1
	v_pk_mul_f32 v[42:43], v[36:37], v[160:161] op_sel_hi:[1,0]
	v_pk_mul_f32 v[36:37], v[34:35], v[160:161] op_sel_hi:[1,0]
	v_cvt_pk_bf16_f32 v34, v38, v39
	v_cvt_pk_bf16_f32 v35, v40, v41
	s_nop 0
	v_cvt_pk_bf16_f32 v36, v36, v37
	v_cvt_pk_bf16_f32 v37, v42, v43
	global_store_dwordx4 v[50:51], v[34:37], off offset:256
	s_nop 1
	v_lshlrev_b64 v[34:35], 11, v[186:187]
	v_lshl_add_u64 v[34:35], s[94:95], 0, v[34:35]
	v_lshl_add_u64 v[34:35], v[34:35], 0, v[146:147]
	v_pk_mul_f32 v[36:37], v[28:29], v[132:133] op_sel_hi:[1,0]
	v_pk_mul_f32 v[28:29], v[26:27], v[132:133] op_sel_hi:[1,0]
	v_cvt_pk_bf16_f32 v26, v30, v31
	v_cvt_pk_bf16_f32 v27, v32, v33
	s_nop 0
	v_cvt_pk_bf16_f32 v28, v28, v29
	v_cvt_pk_bf16_f32 v29, v36, v37
	global_store_dwordx4 v[34:35], v[26:29], off
	s_nop 1
	v_pk_mul_f32 v[26:27], v[20:21], v[132:133] op_sel_hi:[1,0]
	v_pk_mul_f32 v[20:21], v[18:19], v[132:133] op_sel_hi:[1,0]
	v_cvt_pk_bf16_f32 v18, v22, v23
	v_cvt_pk_bf16_f32 v19, v24, v25
	s_nop 0
	v_cvt_pk_bf16_f32 v20, v20, v21
	v_cvt_pk_bf16_f32 v21, v26, v27
	global_store_dwordx4 v[34:35], v[18:21], off offset:256
	s_nop 1
	v_lshlrev_b64 v[18:19], 11, v[184:185]
	v_lshl_add_u64 v[18:19], s[94:95], 0, v[18:19]
	v_lshl_add_u64 v[18:19], v[18:19], 0, v[146:147]
	v_pk_mul_f32 v[20:21], v[12:13], v[130:131] op_sel_hi:[1,0]
	v_pk_mul_f32 v[12:13], v[10:11], v[130:131] op_sel_hi:[1,0]
	v_cvt_pk_bf16_f32 v10, v14, v15
	v_cvt_pk_bf16_f32 v11, v16, v17
	s_nop 0
	v_cvt_pk_bf16_f32 v12, v12, v13
	v_cvt_pk_bf16_f32 v13, v20, v21
	global_store_dwordx4 v[18:19], v[10:13], off
	s_nop 1
	v_pk_mul_f32 v[10:11], v[4:5], v[130:131] op_sel_hi:[1,0]
	v_pk_mul_f32 v[4:5], v[2:3], v[130:131] op_sel_hi:[1,0]
	v_cvt_pk_bf16_f32 v2, v6, v7
	v_cvt_pk_bf16_f32 v3, v8, v9
	s_nop 0
	v_cvt_pk_bf16_f32 v4, v4, v5
	v_cvt_pk_bf16_f32 v5, v10, v11
	global_store_dwordx4 v[18:19], v[2:5], off offset:256
	s_cbranch_vccnz .LBB7_1187
	s_andn2_b64 vcc, exec, s[0:1]
	s_cbranch_vccnz .LBB7_1186
	s_barrier
	s_branch .LBB7_1186
